# removed the per-stage s_setprio flips from all seven GEMM K-loops (timing-only edit)
# speedup vs baseline: 1.0063x; 1.0011x over previous
.LBB0_256:
	v_add_u32_e32 v172, s70, v160
	v_add_u32_e32 v188, s71, v160
	ds_read_b128 v[154:157], v172
	ds_read_b128 v[164:167], v172 offset:1024
	ds_read_b128 v[168:171], v172 offset:2048
	ds_read_b128 v[172:175], v172 offset:3072
	ds_read_b128 v[176:179], v188
	ds_read_b128 v[180:183], v188 offset:1024
	ds_read_b128 v[184:187], v188 offset:2048
	ds_read_b128 v[188:191], v188 offset:3072
	s_add_i32 s75, s30, 2
	s_add_u32 s31, s28, 0xfffc0080
	s_addc_u32 s34, s29, -1
	s_cmp_eq_u32 s67, s30
	s_cselect_b32 s30, s26, s17
	s_cselect_b32 s35, s25, s34
	s_cselect_b32 s34, s24, s31
	s_cselect_b32 s31, s27, s19
	v_lshl_add_u64 v[224:225], s[28:29], 0, v[146:147]
	s_add_i32 m0, s58, 0xc000
	ds_read_b128 v[192:195], v163
	ds_read_b128 v[196:199], v163 offset:1024
	ds_read_b128 v[200:203], v163 offset:2048
	ds_read_b128 v[204:207], v163 offset:3072
	ds_read_b128 v[208:211], v163 offset:4096
	ds_read_b128 v[212:215], v163 offset:5120
	ds_read_b128 v[216:219], v163 offset:6144
	ds_read_b128 v[220:223], v163 offset:7168
	global_load_lds_dwordx4 v[224:225], off
	v_lshl_add_u64 v[224:225], s[28:29], 0, v[148:149]
	s_add_i32 m0, s58, 0xe000
	s_nop 0
	global_load_lds_dwordx4 v[224:225], off
	s_waitcnt vmcnt(8)
	s_waitcnt lgkmcnt(0)
	s_barrier
	s_waitcnt lgkmcnt(0)
	v_mfma_f32_16x16x32_bf16 v[42:45], v[154:157], v[192:195], v[42:45]
	v_mfma_f32_16x16x32_bf16 v[26:29], v[168:171], v[192:195], v[26:29]
	v_mfma_f32_16x16x32_bf16 v[54:57], v[154:157], v[200:203], v[54:57]
	v_mfma_f32_16x16x32_bf16 v[38:41], v[168:171], v[200:203], v[38:41]
	v_mfma_f32_16x16x32_bf16 v[66:69], v[154:157], v[208:211], v[66:69]
	v_mfma_f32_16x16x32_bf16 v[50:53], v[168:171], v[208:211], v[50:53]
	v_mfma_f32_16x16x32_bf16 v[62:65], v[154:157], v[216:219], v[62:65]
	v_mfma_f32_16x16x32_bf16 v[46:49], v[168:171], v[216:219], v[46:49]
	v_mfma_f32_16x16x32_bf16 v[42:45], v[164:167], v[196:199], v[42:45]
	v_mfma_f32_16x16x32_bf16 v[26:29], v[172:175], v[196:199], v[26:29]
	v_mfma_f32_16x16x32_bf16 v[54:57], v[164:167], v[204:207], v[54:57]
	v_mfma_f32_16x16x32_bf16 v[38:41], v[172:175], v[204:207], v[38:41]
	v_mfma_f32_16x16x32_bf16 v[66:69], v[164:167], v[212:215], v[66:69]
	v_mfma_f32_16x16x32_bf16 v[50:53], v[172:175], v[212:215], v[50:53]
	v_mfma_f32_16x16x32_bf16 v[62:65], v[164:167], v[220:223], v[62:65]
	v_mfma_f32_16x16x32_bf16 v[46:49], v[172:175], v[220:223], v[46:49]
	v_mfma_f32_16x16x32_bf16 v[14:17], v[176:179], v[192:195], v[14:17]
	v_mfma_f32_16x16x32_bf16 v[2:5], v[184:187], v[192:195], v[2:5]
	v_mfma_f32_16x16x32_bf16 v[22:25], v[176:179], v[200:203], v[22:25]
	v_mfma_f32_16x16x32_bf16 v[6:9], v[184:187], v[200:203], v[6:9]
	v_mfma_f32_16x16x32_bf16 v[30:33], v[176:179], v[208:211], v[30:33]
	v_mfma_f32_16x16x32_bf16 v[10:13], v[184:187], v[208:211], v[10:13]
	v_mfma_f32_16x16x32_bf16 v[34:37], v[176:179], v[216:219], v[34:37]
	v_mfma_f32_16x16x32_bf16 v[18:21], v[184:187], v[216:219], v[18:21]
	v_mfma_f32_16x16x32_bf16 v[14:17], v[180:183], v[196:199], v[14:17]
	v_mfma_f32_16x16x32_bf16 v[2:5], v[188:191], v[196:199], v[2:5]
	v_mfma_f32_16x16x32_bf16 v[22:25], v[180:183], v[204:207], v[22:25]
	v_mfma_f32_16x16x32_bf16 v[6:9], v[188:191], v[204:207], v[6:9]
	v_mfma_f32_16x16x32_bf16 v[30:33], v[180:183], v[212:215], v[30:33]
	v_mfma_f32_16x16x32_bf16 v[10:13], v[188:191], v[212:215], v[10:13]
	v_mfma_f32_16x16x32_bf16 v[34:37], v[180:183], v[220:223], v[34:37]
	v_mfma_f32_16x16x32_bf16 v[18:21], v[188:191], v[220:223], v[18:21]
	s_barrier
	s_add_i32 s50, s70, s54
	v_lshl_add_u64 v[224:225], s[30:31], 0, v[134:135]
	s_mov_b32 m0, s50
	ds_read_b128 v[192:195], v163 offset:16384
	ds_read_b128 v[196:199], v163 offset:17408
	ds_read_b128 v[200:203], v163 offset:18432
	ds_read_b128 v[204:207], v163 offset:19456
	ds_read_b128 v[208:211], v163 offset:20480
	ds_read_b128 v[212:215], v163 offset:21504
	ds_read_b128 v[216:219], v163 offset:22528
	ds_read_b128 v[220:223], v163 offset:23552
	global_load_lds_dwordx4 v[224:225], off
	s_add_i32 m0, s50, 0x2000
	s_add_u32 s76, s30, 0x40000
	v_lshl_add_u64 v[226:227], s[30:31], 0, v[130:131]
	s_addc_u32 s77, s31, 0
	s_add_i32 s50, s71, s54
	global_load_lds_dwordx4 v[226:227], off
	v_lshl_add_u64 v[228:229], s[76:77], 0, v[134:135]
	s_mov_b32 m0, s50
	v_lshl_add_u64 v[230:231], s[34:35], 0, v[132:133]
	global_load_lds_dwordx4 v[228:229], off
	v_lshl_add_u64 v[228:229], s[76:77], 0, v[130:131]
	s_add_i32 m0, s50, 0x2000
	s_nop 0
	global_load_lds_dwordx4 v[228:229], off
	v_lshl_add_u64 v[228:229], s[34:35], 0, v[136:137]
	s_mov_b32 m0, s58
	s_nop 0
	global_load_lds_dwordx4 v[228:229], off
	s_mov_b32 m0, s59
	s_nop 0
	global_load_lds_dwordx4 v[230:231], off
	s_waitcnt vmcnt(8)
	s_waitcnt lgkmcnt(0)
	s_barrier
	s_waitcnt lgkmcnt(0)
	v_mfma_f32_16x16x32_bf16 v[110:113], v[154:157], v[192:195], v[110:113]
	v_mfma_f32_16x16x32_bf16 v[86:89], v[168:171], v[192:195], v[86:89]
	v_mfma_f32_16x16x32_bf16 v[106:109], v[154:157], v[200:203], v[106:109]
	v_mfma_f32_16x16x32_bf16 v[82:85], v[168:171], v[200:203], v[82:85]
	v_mfma_f32_16x16x32_bf16 v[118:121], v[154:157], v[208:211], v[118:121]
	v_mfma_f32_16x16x32_bf16 v[94:97], v[168:171], v[208:211], v[94:97]
	v_mfma_f32_16x16x32_bf16 v[126:129], v[154:157], v[216:219], v[126:129]
	v_mfma_f32_16x16x32_bf16 v[102:105], v[168:171], v[216:219], v[102:105]
	v_mfma_f32_16x16x32_bf16 v[110:113], v[164:167], v[196:199], v[110:113]
	v_mfma_f32_16x16x32_bf16 v[86:89], v[172:175], v[196:199], v[86:89]
	v_mfma_f32_16x16x32_bf16 v[106:109], v[164:167], v[204:207], v[106:109]
	v_mfma_f32_16x16x32_bf16 v[82:85], v[172:175], v[204:207], v[82:85]
	v_mfma_f32_16x16x32_bf16 v[118:121], v[164:167], v[212:215], v[118:121]
	v_mfma_f32_16x16x32_bf16 v[94:97], v[172:175], v[212:215], v[94:97]
	v_mfma_f32_16x16x32_bf16 v[126:129], v[164:167], v[220:223], v[126:129]
	v_mfma_f32_16x16x32_bf16 v[102:105], v[172:175], v[220:223], v[102:105]
	v_mfma_f32_16x16x32_bf16 v[70:73], v[176:179], v[192:195], v[70:73]
	v_mfma_f32_16x16x32_bf16 v[58:61], v[184:187], v[192:195], v[58:61]
	v_mfma_f32_16x16x32_bf16 v[74:77], v[176:179], v[200:203], v[74:77]
	v_mfma_f32_16x16x32_bf16 v[78:81], v[184:187], v[200:203], v[78:81]
	v_mfma_f32_16x16x32_bf16 v[114:117], v[176:179], v[208:211], v[114:117]
	v_mfma_f32_16x16x32_bf16 v[90:93], v[184:187], v[208:211], v[90:93]
	v_mfma_f32_16x16x32_bf16 v[122:125], v[176:179], v[216:219], v[122:125]
	v_mfma_f32_16x16x32_bf16 v[98:101], v[184:187], v[216:219], v[98:101]
	v_mfma_f32_16x16x32_bf16 v[70:73], v[180:183], v[196:199], v[70:73]
	v_mfma_f32_16x16x32_bf16 v[58:61], v[188:191], v[196:199], v[58:61]
	v_mfma_f32_16x16x32_bf16 v[74:77], v[180:183], v[204:207], v[74:77]
	v_mfma_f32_16x16x32_bf16 v[78:81], v[188:191], v[204:207], v[78:81]
	v_mfma_f32_16x16x32_bf16 v[114:117], v[180:183], v[212:215], v[114:117]
	v_mfma_f32_16x16x32_bf16 v[90:93], v[188:191], v[212:215], v[90:93]
	v_mfma_f32_16x16x32_bf16 v[122:125], v[180:183], v[220:223], v[122:125]
	v_mfma_f32_16x16x32_bf16 v[98:101], v[188:191], v[220:223], v[98:101]
	s_barrier
	s_add_i32 s50, 0, 0x18000
	s_add_i32 s51, 0, 0x1c000
	v_add_u32_e32 v172, s50, v160
	v_add_u32_e32 v188, s51, v160
	ds_read_b128 v[154:157], v172
	ds_read_b128 v[164:167], v172 offset:1024
	ds_read_b128 v[168:171], v172 offset:2048
	ds_read_b128 v[172:175], v172 offset:3072
	ds_read_b128 v[176:179], v188
	ds_read_b128 v[180:183], v188 offset:1024
	ds_read_b128 v[184:187], v188 offset:2048
	ds_read_b128 v[188:191], v188 offset:3072
	s_add_u32 s34, s34, 0x40000
	s_addc_u32 s35, s35, 0
	s_mov_b32 m0, s60
	v_lshl_add_u64 v[232:233], s[34:35], 0, v[136:137]
	ds_read_b128 v[192:195], v163 offset:32768
	ds_read_b128 v[196:199], v163 offset:33792
	ds_read_b128 v[200:203], v163 offset:34816
	ds_read_b128 v[204:207], v163 offset:35840
	ds_read_b128 v[208:211], v163 offset:36864
	ds_read_b128 v[212:215], v163 offset:37888
	ds_read_b128 v[216:219], v163 offset:38912
	ds_read_b128 v[220:223], v163 offset:39936
	global_load_lds_dwordx4 v[232:233], off
	v_lshl_add_u64 v[232:233], s[34:35], 0, v[132:133]
	s_mov_b32 m0, s61
	s_nop 0
	global_load_lds_dwordx4 v[232:233], off
	s_waitcnt vmcnt(8)
	s_waitcnt lgkmcnt(0)
	s_barrier
	s_waitcnt lgkmcnt(0)
	v_mfma_f32_16x16x32_bf16 v[42:45], v[154:157], v[192:195], v[42:45]
	v_mfma_f32_16x16x32_bf16 v[26:29], v[168:171], v[192:195], v[26:29]
	v_mfma_f32_16x16x32_bf16 v[54:57], v[154:157], v[200:203], v[54:57]
	v_mfma_f32_16x16x32_bf16 v[38:41], v[168:171], v[200:203], v[38:41]
	v_mfma_f32_16x16x32_bf16 v[66:69], v[154:157], v[208:211], v[66:69]
	v_mfma_f32_16x16x32_bf16 v[50:53], v[168:171], v[208:211], v[50:53]
	v_mfma_f32_16x16x32_bf16 v[62:65], v[154:157], v[216:219], v[62:65]
	v_mfma_f32_16x16x32_bf16 v[46:49], v[168:171], v[216:219], v[46:49]
	v_mfma_f32_16x16x32_bf16 v[42:45], v[164:167], v[196:199], v[42:45]
	v_mfma_f32_16x16x32_bf16 v[26:29], v[172:175], v[196:199], v[26:29]
	v_mfma_f32_16x16x32_bf16 v[54:57], v[164:167], v[204:207], v[54:57]
	v_mfma_f32_16x16x32_bf16 v[38:41], v[172:175], v[204:207], v[38:41]
	v_mfma_f32_16x16x32_bf16 v[66:69], v[164:167], v[212:215], v[66:69]
	v_mfma_f32_16x16x32_bf16 v[50:53], v[172:175], v[212:215], v[50:53]
	v_mfma_f32_16x16x32_bf16 v[62:65], v[164:167], v[220:223], v[62:65]
	v_mfma_f32_16x16x32_bf16 v[46:49], v[172:175], v[220:223], v[46:49]
	v_mfma_f32_16x16x32_bf16 v[14:17], v[176:179], v[192:195], v[14:17]
	v_mfma_f32_16x16x32_bf16 v[2:5], v[184:187], v[192:195], v[2:5]
	v_mfma_f32_16x16x32_bf16 v[22:25], v[176:179], v[200:203], v[22:25]
	v_mfma_f32_16x16x32_bf16 v[6:9], v[184:187], v[200:203], v[6:9]
	v_mfma_f32_16x16x32_bf16 v[30:33], v[176:179], v[208:211], v[30:33]
	v_mfma_f32_16x16x32_bf16 v[10:13], v[184:187], v[208:211], v[10:13]
	v_mfma_f32_16x16x32_bf16 v[34:37], v[176:179], v[216:219], v[34:37]
	v_mfma_f32_16x16x32_bf16 v[18:21], v[184:187], v[216:219], v[18:21]
	v_mfma_f32_16x16x32_bf16 v[14:17], v[180:183], v[196:199], v[14:17]
	v_mfma_f32_16x16x32_bf16 v[2:5], v[188:191], v[196:199], v[2:5]
	v_mfma_f32_16x16x32_bf16 v[22:25], v[180:183], v[204:207], v[22:25]
	v_mfma_f32_16x16x32_bf16 v[6:9], v[188:191], v[204:207], v[6:9]
	v_mfma_f32_16x16x32_bf16 v[30:33], v[180:183], v[212:215], v[30:33]
	v_mfma_f32_16x16x32_bf16 v[10:13], v[188:191], v[212:215], v[10:13]
	v_mfma_f32_16x16x32_bf16 v[34:37], v[180:183], v[220:223], v[34:37]
	v_mfma_f32_16x16x32_bf16 v[18:21], v[188:191], v[220:223], v[18:21]
	s_barrier
	s_add_i32 s34, s50, s54
	v_lshl_add_u64 v[224:225], v[224:225], 0, s[10:11]
	s_mov_b32 m0, s34
	ds_read_b128 v[192:195], v163 offset:49152
	ds_read_b128 v[196:199], v163 offset:50176
	ds_read_b128 v[200:203], v163 offset:51200
	ds_read_b128 v[204:207], v163 offset:52224
	ds_read_b128 v[208:211], v163 offset:53248
	ds_read_b128 v[212:215], v163 offset:54272
	ds_read_b128 v[216:219], v163 offset:55296
	ds_read_b128 v[220:223], v163 offset:56320
	global_load_lds_dwordx4 v[224:225], off
	s_add_i32 m0, s34, 0x2000
	s_add_u32 s30, s30, 0x40080
	v_lshl_add_u64 v[224:225], v[226:227], 0, s[10:11]
	s_addc_u32 s31, s31, 0
	s_add_i32 s34, s51, s54
	global_load_lds_dwordx4 v[224:225], off
	v_lshl_add_u64 v[224:225], s[30:31], 0, v[134:135]
	s_mov_b32 m0, s34
	s_nop 0
	global_load_lds_dwordx4 v[224:225], off
	v_lshl_add_u64 v[224:225], s[30:31], 0, v[130:131]
	s_add_i32 m0, s34, 0x2000
	s_nop 0
	global_load_lds_dwordx4 v[224:225], off
	v_lshl_add_u64 v[224:225], v[228:229], 0, s[10:11]
	s_mov_b32 m0, s65
	s_nop 0
	global_load_lds_dwordx4 v[224:225], off
	v_lshl_add_u64 v[224:225], v[230:231], 0, s[10:11]
	s_mov_b32 m0, s66
	s_nop 0
	global_load_lds_dwordx4 v[224:225], off
	s_waitcnt vmcnt(8)
	s_waitcnt lgkmcnt(0)
	s_barrier
	s_waitcnt lgkmcnt(0)
	v_mfma_f32_16x16x32_bf16 v[110:113], v[154:157], v[192:195], v[110:113]
	v_mfma_f32_16x16x32_bf16 v[86:89], v[168:171], v[192:195], v[86:89]
	v_mfma_f32_16x16x32_bf16 v[106:109], v[154:157], v[200:203], v[106:109]
	v_mfma_f32_16x16x32_bf16 v[82:85], v[168:171], v[200:203], v[82:85]
	v_mfma_f32_16x16x32_bf16 v[118:121], v[154:157], v[208:211], v[118:121]
	v_mfma_f32_16x16x32_bf16 v[94:97], v[168:171], v[208:211], v[94:97]
	v_mfma_f32_16x16x32_bf16 v[126:129], v[154:157], v[216:219], v[126:129]
	v_mfma_f32_16x16x32_bf16 v[102:105], v[168:171], v[216:219], v[102:105]
	v_mfma_f32_16x16x32_bf16 v[110:113], v[164:167], v[196:199], v[110:113]
	v_mfma_f32_16x16x32_bf16 v[86:89], v[172:175], v[196:199], v[86:89]
	v_mfma_f32_16x16x32_bf16 v[106:109], v[164:167], v[204:207], v[106:109]
	v_mfma_f32_16x16x32_bf16 v[82:85], v[172:175], v[204:207], v[82:85]
	v_mfma_f32_16x16x32_bf16 v[118:121], v[164:167], v[212:215], v[118:121]
	v_mfma_f32_16x16x32_bf16 v[94:97], v[172:175], v[212:215], v[94:97]
	v_mfma_f32_16x16x32_bf16 v[126:129], v[164:167], v[220:223], v[126:129]
	v_mfma_f32_16x16x32_bf16 v[102:105], v[172:175], v[220:223], v[102:105]
	v_mfma_f32_16x16x32_bf16 v[70:73], v[176:179], v[192:195], v[70:73]
	v_mfma_f32_16x16x32_bf16 v[58:61], v[184:187], v[192:195], v[58:61]
	v_mfma_f32_16x16x32_bf16 v[74:77], v[176:179], v[200:203], v[74:77]
	v_mfma_f32_16x16x32_bf16 v[78:81], v[184:187], v[200:203], v[78:81]
	v_mfma_f32_16x16x32_bf16 v[114:117], v[176:179], v[208:211], v[114:117]
	v_mfma_f32_16x16x32_bf16 v[90:93], v[184:187], v[208:211], v[90:93]
	v_mfma_f32_16x16x32_bf16 v[122:125], v[176:179], v[216:219], v[122:125]
	v_mfma_f32_16x16x32_bf16 v[98:101], v[184:187], v[216:219], v[98:101]
	v_mfma_f32_16x16x32_bf16 v[70:73], v[180:183], v[196:199], v[70:73]
	v_mfma_f32_16x16x32_bf16 v[58:61], v[188:191], v[196:199], v[58:61]
	v_mfma_f32_16x16x32_bf16 v[74:77], v[180:183], v[204:207], v[74:77]
	v_mfma_f32_16x16x32_bf16 v[78:81], v[188:191], v[204:207], v[78:81]
	v_mfma_f32_16x16x32_bf16 v[114:117], v[180:183], v[212:215], v[114:117]
	v_mfma_f32_16x16x32_bf16 v[90:93], v[188:191], v[212:215], v[90:93]
	v_mfma_f32_16x16x32_bf16 v[122:125], v[180:183], v[220:223], v[122:125]
	v_mfma_f32_16x16x32_bf16 v[98:101], v[188:191], v[220:223], v[98:101]
	s_barrier
	s_add_u32 s28, s28, 0x100
	s_addc_u32 s29, s29, 0
	s_add_u32 s17, s17, 0x100
	s_addc_u32 s19, s19, 0
	s_cmp_ge_i32 s75, s62
	s_mov_b32 s30, s75
	s_cbranch_scc0 .LBB0_256

.LBB0_351:
	v_add_u32_e32 v81, s62, v78
	s_waitcnt lgkmcnt(0)
	ds_read_b128 v[82:85], v81
	ds_read_b128 v[86:89], v81 offset:1024
	ds_read_b128 v[90:93], v81 offset:2048
	ds_read_b128 v[94:97], v81 offset:3072
	s_add_i32 s72, s24, 2
	s_add_u32 s22, s20, 0x100
	s_addc_u32 s23, s21, 0
	s_cmp_eq_u32 s61, s24
	s_cselect_b32 s24, s16, s70
	s_cselect_b32 s27, s15, s23
	s_cselect_b32 s26, s14, s22
	s_cselect_b32 s25, s17, s71
	s_mov_b32 m0, s63
	v_lshl_add_u64 v[130:131], s[20:21], 0, v[74:75]
	ds_read_b128 v[98:101], v79
	ds_read_b128 v[102:105], v79 offset:1024
	ds_read_b128 v[106:109], v79 offset:2048
	ds_read_b128 v[110:113], v79 offset:3072
	ds_read_b128 v[114:117], v79 offset:4096
	ds_read_b128 v[118:121], v79 offset:5120
	ds_read_b128 v[122:125], v79 offset:6144
	ds_read_b128 v[126:129], v79 offset:7168
	global_load_lds_dwordx4 v[130:131], off
	v_lshl_add_u64 v[130:131], s[20:21], 0, v[76:77]
	s_mov_b32 m0, s64
	s_nop 0
	global_load_lds_dwordx4 v[130:131], off
	s_waitcnt vmcnt(8)
	s_waitcnt lgkmcnt(0)
	s_barrier
	s_waitcnt lgkmcnt(0)
	v_mfma_f32_16x16x32_bf16 v[62:65], v[82:85], v[98:101], v[62:65]
	v_mfma_f32_16x16x32_bf16 v[58:61], v[90:93], v[98:101], v[58:61]
	v_mfma_f32_16x16x32_bf16 v[54:57], v[82:85], v[106:109], v[54:57]
	v_mfma_f32_16x16x32_bf16 v[50:53], v[90:93], v[106:109], v[50:53]
	v_mfma_f32_16x16x32_bf16 v[46:49], v[82:85], v[114:117], v[46:49]
	v_mfma_f32_16x16x32_bf16 v[42:45], v[90:93], v[114:117], v[42:45]
	v_mfma_f32_16x16x32_bf16 v[34:37], v[82:85], v[122:125], v[34:37]
	v_mfma_f32_16x16x32_bf16 v[26:29], v[90:93], v[122:125], v[26:29]
	v_mfma_f32_16x16x32_bf16 v[62:65], v[86:89], v[102:105], v[62:65]
	v_mfma_f32_16x16x32_bf16 v[58:61], v[94:97], v[102:105], v[58:61]
	v_mfma_f32_16x16x32_bf16 v[54:57], v[86:89], v[110:113], v[54:57]
	v_mfma_f32_16x16x32_bf16 v[50:53], v[94:97], v[110:113], v[50:53]
	v_mfma_f32_16x16x32_bf16 v[46:49], v[86:89], v[118:121], v[46:49]
	v_mfma_f32_16x16x32_bf16 v[42:45], v[94:97], v[118:121], v[42:45]
	v_mfma_f32_16x16x32_bf16 v[34:37], v[86:89], v[126:129], v[34:37]
	v_mfma_f32_16x16x32_bf16 v[26:29], v[94:97], v[126:129], v[26:29]
	s_barrier
	s_mov_b32 m0, s65
	v_lshl_add_u64 v[130:131], s[24:25], 0, v[70:71]
	s_add_u32 s20, s24, 0x10000
	ds_read_b128 v[98:101], v79 offset:16384
	ds_read_b128 v[102:105], v79 offset:17408
	ds_read_b128 v[106:109], v79 offset:18432
	ds_read_b128 v[110:113], v79 offset:19456
	ds_read_b128 v[114:117], v79 offset:20480
	ds_read_b128 v[118:121], v79 offset:21504
	ds_read_b128 v[122:125], v79 offset:22528
	ds_read_b128 v[126:129], v79 offset:23552
	global_load_lds_dwordx4 v[130:131], off
	v_lshl_add_u64 v[132:133], s[24:25], 0, v[66:67]
	s_mov_b32 m0, s66
	s_addc_u32 s21, s25, 0
	global_load_lds_dwordx4 v[132:133], off
	v_lshl_add_u64 v[134:135], s[20:21], 0, v[70:71]
	s_mov_b32 m0, s34
	v_lshl_add_u64 v[136:137], s[26:27], 0, v[68:69]
	global_load_lds_dwordx4 v[134:135], off
	v_lshl_add_u64 v[134:135], s[20:21], 0, v[66:67]
	s_mov_b32 m0, s35
	s_nop 0
	global_load_lds_dwordx4 v[134:135], off
	v_lshl_add_u64 v[134:135], s[26:27], 0, v[72:73]
	s_mov_b32 m0, s31
	s_nop 0
	global_load_lds_dwordx4 v[134:135], off
	s_mov_b32 m0, s52
	s_nop 0
	global_load_lds_dwordx4 v[136:137], off
	s_waitcnt vmcnt(8)
	s_waitcnt lgkmcnt(0)
	s_barrier
	s_waitcnt lgkmcnt(0)
	v_mfma_f32_16x16x32_bf16 v[38:41], v[82:85], v[98:101], v[38:41]
	v_mfma_f32_16x16x32_bf16 v[30:33], v[90:93], v[98:101], v[30:33]
	v_mfma_f32_16x16x32_bf16 v[22:25], v[82:85], v[106:109], v[22:25]
	v_mfma_f32_16x16x32_bf16 v[18:21], v[90:93], v[106:109], v[18:21]
	v_mfma_f32_16x16x32_bf16 v[14:17], v[82:85], v[114:117], v[14:17]
	v_mfma_f32_16x16x32_bf16 v[10:13], v[90:93], v[114:117], v[10:13]
	v_mfma_f32_16x16x32_bf16 v[6:9], v[82:85], v[122:125], v[6:9]
	v_mfma_f32_16x16x32_bf16 v[2:5], v[90:93], v[122:125], v[2:5]
	v_mfma_f32_16x16x32_bf16 v[38:41], v[86:89], v[102:105], v[38:41]
	v_mfma_f32_16x16x32_bf16 v[30:33], v[94:97], v[102:105], v[30:33]
	v_mfma_f32_16x16x32_bf16 v[22:25], v[86:89], v[110:113], v[22:25]
	v_mfma_f32_16x16x32_bf16 v[18:21], v[94:97], v[110:113], v[18:21]
	v_mfma_f32_16x16x32_bf16 v[14:17], v[86:89], v[118:121], v[14:17]
	v_mfma_f32_16x16x32_bf16 v[10:13], v[94:97], v[118:121], v[10:13]
	v_mfma_f32_16x16x32_bf16 v[6:9], v[86:89], v[126:129], v[6:9]
	v_mfma_f32_16x16x32_bf16 v[2:5], v[94:97], v[126:129], v[2:5]
	s_barrier
	v_add_u32_e32 v81, s67, v78
	ds_read_b128 v[82:85], v81
	ds_read_b128 v[86:89], v81 offset:1024
	ds_read_b128 v[90:93], v81 offset:2048
	ds_read_b128 v[94:97], v81 offset:3072
	s_add_u32 s20, s26, 0x18000
	s_addc_u32 s21, s27, 0
	s_mov_b32 m0, s53
	v_lshl_add_u64 v[138:139], s[20:21], 0, v[72:73]
	ds_read_b128 v[98:101], v79 offset:32768
	ds_read_b128 v[102:105], v79 offset:33792
	ds_read_b128 v[106:109], v79 offset:34816
	ds_read_b128 v[110:113], v79 offset:35840
	ds_read_b128 v[114:117], v79 offset:36864
	ds_read_b128 v[118:121], v79 offset:37888
	ds_read_b128 v[122:125], v79 offset:38912
	ds_read_b128 v[126:129], v79 offset:39936
	global_load_lds_dwordx4 v[138:139], off
	v_lshl_add_u64 v[138:139], s[20:21], 0, v[68:69]
	s_mov_b32 m0, s54
	s_nop 0
	global_load_lds_dwordx4 v[138:139], off
	s_waitcnt vmcnt(8)
	s_waitcnt lgkmcnt(0)
	s_barrier
	s_waitcnt lgkmcnt(0)
	v_mfma_f32_16x16x32_bf16 v[62:65], v[82:85], v[98:101], v[62:65]
	v_mfma_f32_16x16x32_bf16 v[58:61], v[90:93], v[98:101], v[58:61]
	v_mfma_f32_16x16x32_bf16 v[54:57], v[82:85], v[106:109], v[54:57]
	v_mfma_f32_16x16x32_bf16 v[50:53], v[90:93], v[106:109], v[50:53]
	v_mfma_f32_16x16x32_bf16 v[46:49], v[82:85], v[114:117], v[46:49]
	v_mfma_f32_16x16x32_bf16 v[42:45], v[90:93], v[114:117], v[42:45]
	v_mfma_f32_16x16x32_bf16 v[34:37], v[82:85], v[122:125], v[34:37]
	v_mfma_f32_16x16x32_bf16 v[26:29], v[90:93], v[122:125], v[26:29]
	v_mfma_f32_16x16x32_bf16 v[62:65], v[86:89], v[102:105], v[62:65]
	v_mfma_f32_16x16x32_bf16 v[58:61], v[94:97], v[102:105], v[58:61]
	v_mfma_f32_16x16x32_bf16 v[54:57], v[86:89], v[110:113], v[54:57]
	v_mfma_f32_16x16x32_bf16 v[50:53], v[94:97], v[110:113], v[50:53]
	v_mfma_f32_16x16x32_bf16 v[46:49], v[86:89], v[118:121], v[46:49]
	v_mfma_f32_16x16x32_bf16 v[42:45], v[94:97], v[118:121], v[42:45]
	v_mfma_f32_16x16x32_bf16 v[34:37], v[86:89], v[126:129], v[34:37]
	v_mfma_f32_16x16x32_bf16 v[26:29], v[94:97], v[126:129], v[26:29]
	s_barrier
	s_mov_b32 m0, s68
	v_lshl_add_u64 v[130:131], v[130:131], 0, s[6:7]
	s_add_u32 s20, s24, 0x10080
	ds_read_b128 v[98:101], v79 offset:49152
	ds_read_b128 v[102:105], v79 offset:50176
	ds_read_b128 v[106:109], v79 offset:51200
	ds_read_b128 v[110:113], v79 offset:52224
	ds_read_b128 v[114:117], v79 offset:53248
	ds_read_b128 v[118:121], v79 offset:54272
	ds_read_b128 v[122:125], v79 offset:55296
	ds_read_b128 v[126:129], v79 offset:56320
	global_load_lds_dwordx4 v[130:131], off
	v_lshl_add_u64 v[130:131], v[132:133], 0, s[6:7]
	s_mov_b32 m0, s69
	s_addc_u32 s21, s25, 0
	global_load_lds_dwordx4 v[130:131], off
	v_lshl_add_u64 v[130:131], s[20:21], 0, v[70:71]
	s_mov_b32 m0, s59
	s_nop 0
	global_load_lds_dwordx4 v[130:131], off
	v_lshl_add_u64 v[130:131], s[20:21], 0, v[66:67]
	s_mov_b32 m0, s60
	s_nop 0
	global_load_lds_dwordx4 v[130:131], off
	v_lshl_add_u64 v[130:131], v[134:135], 0, s[6:7]
	s_mov_b32 m0, s57
	s_nop 0
	global_load_lds_dwordx4 v[130:131], off
	v_lshl_add_u64 v[130:131], v[136:137], 0, s[6:7]
	s_mov_b32 m0, s58
	s_nop 0
	global_load_lds_dwordx4 v[130:131], off
	s_waitcnt vmcnt(8)
	s_waitcnt lgkmcnt(0)
	s_barrier
	s_waitcnt lgkmcnt(0)
	v_mfma_f32_16x16x32_bf16 v[38:41], v[82:85], v[98:101], v[38:41]
	v_mfma_f32_16x16x32_bf16 v[30:33], v[90:93], v[98:101], v[30:33]
	v_mfma_f32_16x16x32_bf16 v[22:25], v[82:85], v[106:109], v[22:25]
	v_mfma_f32_16x16x32_bf16 v[18:21], v[90:93], v[106:109], v[18:21]
	v_mfma_f32_16x16x32_bf16 v[14:17], v[82:85], v[114:117], v[14:17]
	v_mfma_f32_16x16x32_bf16 v[10:13], v[90:93], v[114:117], v[10:13]
	v_mfma_f32_16x16x32_bf16 v[6:9], v[82:85], v[122:125], v[6:9]
	v_mfma_f32_16x16x32_bf16 v[2:5], v[90:93], v[122:125], v[2:5]
	v_mfma_f32_16x16x32_bf16 v[38:41], v[86:89], v[102:105], v[38:41]
	v_mfma_f32_16x16x32_bf16 v[30:33], v[94:97], v[102:105], v[30:33]
	v_mfma_f32_16x16x32_bf16 v[22:25], v[86:89], v[110:113], v[22:25]
	v_mfma_f32_16x16x32_bf16 v[18:21], v[94:97], v[110:113], v[18:21]
	v_mfma_f32_16x16x32_bf16 v[14:17], v[86:89], v[118:121], v[14:17]
	v_mfma_f32_16x16x32_bf16 v[10:13], v[94:97], v[118:121], v[10:13]
	v_mfma_f32_16x16x32_bf16 v[6:9], v[86:89], v[126:129], v[6:9]
	v_mfma_f32_16x16x32_bf16 v[2:5], v[94:97], v[126:129], v[2:5]
	s_barrier
	s_add_u32 s70, s70, 0x100
	s_addc_u32 s71, s71, 0
	s_cmp_ge_i32 s72, s56
	s_mov_b64 s[20:21], s[22:23]
	s_mov_b32 s24, s72
	s_cbranch_scc0 .LBB0_351

.LBB0_468:
	v_add_u32_e32 v144, s62, v1
	ds_read_b128 v[150:153], v144
	ds_read_b128 v[154:157], v144 offset:1024
	ds_read_b128 v[158:161], v144 offset:2048
	ds_read_b128 v[162:165], v144 offset:3072
	v_add_u32_e32 v144, s63, v1
	ds_read_b128 v[166:169], v144
	ds_read_b128 v[170:173], v144 offset:1024
	ds_read_b128 v[174:177], v144 offset:2048
	ds_read_b128 v[178:181], v144 offset:3072
	s_add_i32 s77, s26, 2
	s_add_u32 s24, s22, 0x100
	s_addc_u32 s25, s23, 0
	s_cmp_eq_u32 s61, s26
	s_cselect_b32 s26, s16, s75
	s_cselect_b32 s29, s15, s25
	s_cselect_b32 s28, s14, s24
	s_cselect_b32 s27, s17, s76
	s_mov_b32 m0, s64
	v_lshl_add_u64 v[144:145], s[22:23], 0, v[140:141]
	ds_read_b128 v[182:185], v149
	ds_read_b128 v[186:189], v149 offset:1024
	ds_read_b128 v[190:193], v149 offset:2048
	ds_read_b128 v[194:197], v149 offset:3072
	ds_read_b128 v[198:201], v149 offset:4096
	ds_read_b128 v[202:205], v149 offset:5120
	ds_read_b128 v[206:209], v149 offset:6144
	ds_read_b128 v[210:213], v149 offset:7168
	global_load_lds_dwordx4 v[144:145], off
	v_lshl_add_u64 v[144:145], s[22:23], 0, v[142:143]
	s_mov_b32 m0, s65
	s_nop 0
	global_load_lds_dwordx4 v[144:145], off
	s_waitcnt vmcnt(8)
	s_waitcnt lgkmcnt(0)
	s_barrier
	s_waitcnt lgkmcnt(0)
	v_mfma_f32_16x16x32_bf16 v[126:129], v[150:153], v[182:185], v[126:129]
	v_mfma_f32_16x16x32_bf16 v[122:125], v[158:161], v[182:185], v[122:125]
	v_mfma_f32_16x16x32_bf16 v[110:113], v[150:153], v[190:193], v[110:113]
	v_mfma_f32_16x16x32_bf16 v[106:109], v[158:161], v[190:193], v[106:109]
	v_mfma_f32_16x16x32_bf16 v[94:97], v[150:153], v[198:201], v[94:97]
	v_mfma_f32_16x16x32_bf16 v[90:93], v[158:161], v[198:201], v[90:93]
	v_mfma_f32_16x16x32_bf16 v[78:81], v[150:153], v[206:209], v[78:81]
	v_mfma_f32_16x16x32_bf16 v[74:77], v[158:161], v[206:209], v[74:77]
	v_mfma_f32_16x16x32_bf16 v[126:129], v[154:157], v[186:189], v[126:129]
	v_mfma_f32_16x16x32_bf16 v[122:125], v[162:165], v[186:189], v[122:125]
	v_mfma_f32_16x16x32_bf16 v[110:113], v[154:157], v[194:197], v[110:113]
	v_mfma_f32_16x16x32_bf16 v[106:109], v[162:165], v[194:197], v[106:109]
	v_mfma_f32_16x16x32_bf16 v[94:97], v[154:157], v[202:205], v[94:97]
	v_mfma_f32_16x16x32_bf16 v[90:93], v[162:165], v[202:205], v[90:93]
	v_mfma_f32_16x16x32_bf16 v[78:81], v[154:157], v[210:213], v[78:81]
	v_mfma_f32_16x16x32_bf16 v[74:77], v[162:165], v[210:213], v[74:77]
	v_mfma_f32_16x16x32_bf16 v[118:121], v[166:169], v[182:185], v[118:121]
	v_mfma_f32_16x16x32_bf16 v[114:117], v[174:177], v[182:185], v[114:117]
	v_mfma_f32_16x16x32_bf16 v[102:105], v[166:169], v[190:193], v[102:105]
	v_mfma_f32_16x16x32_bf16 v[98:101], v[174:177], v[190:193], v[98:101]
	v_mfma_f32_16x16x32_bf16 v[86:89], v[166:169], v[198:201], v[86:89]
	v_mfma_f32_16x16x32_bf16 v[82:85], v[174:177], v[198:201], v[82:85]
	v_mfma_f32_16x16x32_bf16 v[70:73], v[166:169], v[206:209], v[70:73]
	v_mfma_f32_16x16x32_bf16 v[66:69], v[174:177], v[206:209], v[66:69]
	v_mfma_f32_16x16x32_bf16 v[118:121], v[170:173], v[186:189], v[118:121]
	v_mfma_f32_16x16x32_bf16 v[114:117], v[178:181], v[186:189], v[114:117]
	v_mfma_f32_16x16x32_bf16 v[102:105], v[170:173], v[194:197], v[102:105]
	v_mfma_f32_16x16x32_bf16 v[98:101], v[178:181], v[194:197], v[98:101]
	v_mfma_f32_16x16x32_bf16 v[86:89], v[170:173], v[202:205], v[86:89]
	v_mfma_f32_16x16x32_bf16 v[82:85], v[178:181], v[202:205], v[82:85]
	v_mfma_f32_16x16x32_bf16 v[70:73], v[170:173], v[210:213], v[70:73]
	v_mfma_f32_16x16x32_bf16 v[66:69], v[178:181], v[210:213], v[66:69]
	s_barrier
	s_mov_b32 m0, s66
	v_lshl_add_u64 v[144:145], s[26:27], 0, v[134:135]
	s_add_u32 s22, s26, 0x18000
	ds_read_b128 v[182:185], v149 offset:16384
	ds_read_b128 v[186:189], v149 offset:17408
	ds_read_b128 v[190:193], v149 offset:18432
	ds_read_b128 v[194:197], v149 offset:19456
	ds_read_b128 v[198:201], v149 offset:20480
	ds_read_b128 v[202:205], v149 offset:21504
	ds_read_b128 v[206:209], v149 offset:22528
	ds_read_b128 v[210:213], v149 offset:23552
	global_load_lds_dwordx4 v[144:145], off
	v_lshl_add_u64 v[214:215], s[26:27], 0, v[130:131]
	s_mov_b32 m0, s67
	s_addc_u32 s23, s27, 0
	global_load_lds_dwordx4 v[214:215], off
	v_lshl_add_u64 v[216:217], s[22:23], 0, v[134:135]
	s_mov_b32 m0, s68
	v_lshl_add_u64 v[218:219], s[28:29], 0, v[132:133]
	global_load_lds_dwordx4 v[216:217], off
	v_lshl_add_u64 v[216:217], s[22:23], 0, v[130:131]
	s_mov_b32 m0, s69
	s_nop 0
	global_load_lds_dwordx4 v[216:217], off
	v_lshl_add_u64 v[216:217], s[28:29], 0, v[136:137]
	s_mov_b32 m0, s34
	s_nop 0
	global_load_lds_dwordx4 v[216:217], off
	s_mov_b32 m0, s35
	s_nop 0
	global_load_lds_dwordx4 v[218:219], off
	s_waitcnt vmcnt(8)
	s_waitcnt lgkmcnt(0)
	s_barrier
	s_waitcnt lgkmcnt(0)
	v_mfma_f32_16x16x32_bf16 v[62:65], v[150:153], v[182:185], v[62:65]
	v_mfma_f32_16x16x32_bf16 v[58:61], v[158:161], v[182:185], v[58:61]
	v_mfma_f32_16x16x32_bf16 v[46:49], v[150:153], v[190:193], v[46:49]
	v_mfma_f32_16x16x32_bf16 v[42:45], v[158:161], v[190:193], v[42:45]
	v_mfma_f32_16x16x32_bf16 v[30:33], v[150:153], v[198:201], v[30:33]
	v_mfma_f32_16x16x32_bf16 v[26:29], v[158:161], v[198:201], v[26:29]
	v_mfma_f32_16x16x32_bf16 v[14:17], v[150:153], v[206:209], v[14:17]
	v_mfma_f32_16x16x32_bf16 v[10:13], v[158:161], v[206:209], v[10:13]
	v_mfma_f32_16x16x32_bf16 v[62:65], v[154:157], v[186:189], v[62:65]
	v_mfma_f32_16x16x32_bf16 v[58:61], v[162:165], v[186:189], v[58:61]
	v_mfma_f32_16x16x32_bf16 v[46:49], v[154:157], v[194:197], v[46:49]
	v_mfma_f32_16x16x32_bf16 v[42:45], v[162:165], v[194:197], v[42:45]
	v_mfma_f32_16x16x32_bf16 v[30:33], v[154:157], v[202:205], v[30:33]
	v_mfma_f32_16x16x32_bf16 v[26:29], v[162:165], v[202:205], v[26:29]
	v_mfma_f32_16x16x32_bf16 v[14:17], v[154:157], v[210:213], v[14:17]
	v_mfma_f32_16x16x32_bf16 v[10:13], v[162:165], v[210:213], v[10:13]
	v_mfma_f32_16x16x32_bf16 v[54:57], v[166:169], v[182:185], v[54:57]
	v_mfma_f32_16x16x32_bf16 v[50:53], v[174:177], v[182:185], v[50:53]
	v_mfma_f32_16x16x32_bf16 v[38:41], v[166:169], v[190:193], v[38:41]
	v_mfma_f32_16x16x32_bf16 v[34:37], v[174:177], v[190:193], v[34:37]
	v_mfma_f32_16x16x32_bf16 v[22:25], v[166:169], v[198:201], v[22:25]
	v_mfma_f32_16x16x32_bf16 v[18:21], v[174:177], v[198:201], v[18:21]
	v_mfma_f32_16x16x32_bf16 v[6:9], v[166:169], v[206:209], v[6:9]
	v_mfma_f32_16x16x32_bf16 v[2:5], v[174:177], v[206:209], v[2:5]
	v_mfma_f32_16x16x32_bf16 v[54:57], v[170:173], v[186:189], v[54:57]
	v_mfma_f32_16x16x32_bf16 v[50:53], v[178:181], v[186:189], v[50:53]
	v_mfma_f32_16x16x32_bf16 v[38:41], v[170:173], v[194:197], v[38:41]
	v_mfma_f32_16x16x32_bf16 v[34:37], v[178:181], v[194:197], v[34:37]
	v_mfma_f32_16x16x32_bf16 v[22:25], v[170:173], v[202:205], v[22:25]
	v_mfma_f32_16x16x32_bf16 v[18:21], v[178:181], v[202:205], v[18:21]
	v_mfma_f32_16x16x32_bf16 v[6:9], v[170:173], v[210:213], v[6:9]
	v_mfma_f32_16x16x32_bf16 v[2:5], v[178:181], v[210:213], v[2:5]
	s_barrier
	v_add_u32_e32 v162, s70, v1
	v_add_u32_e32 v178, s71, v1
	ds_read_b128 v[150:153], v162
	ds_read_b128 v[154:157], v162 offset:1024
	ds_read_b128 v[158:161], v162 offset:2048
	ds_read_b128 v[162:165], v162 offset:3072
	ds_read_b128 v[166:169], v178
	ds_read_b128 v[170:173], v178 offset:1024
	ds_read_b128 v[174:177], v178 offset:2048
	ds_read_b128 v[178:181], v178 offset:3072
	s_add_u32 s22, s28, 0x18000
	s_addc_u32 s23, s29, 0
	s_mov_b32 m0, s52
	v_lshl_add_u64 v[220:221], s[22:23], 0, v[136:137]
	ds_read_b128 v[182:185], v149 offset:32768
	ds_read_b128 v[186:189], v149 offset:33792
	ds_read_b128 v[190:193], v149 offset:34816
	ds_read_b128 v[194:197], v149 offset:35840
	ds_read_b128 v[198:201], v149 offset:36864
	ds_read_b128 v[202:205], v149 offset:37888
	ds_read_b128 v[206:209], v149 offset:38912
	ds_read_b128 v[210:213], v149 offset:39936
	global_load_lds_dwordx4 v[220:221], off
	v_lshl_add_u64 v[220:221], s[22:23], 0, v[132:133]
	s_mov_b32 m0, s53
	s_nop 0
	global_load_lds_dwordx4 v[220:221], off
	s_waitcnt vmcnt(8)
	s_waitcnt lgkmcnt(0)
	s_barrier
	s_waitcnt lgkmcnt(0)
	v_mfma_f32_16x16x32_bf16 v[126:129], v[150:153], v[182:185], v[126:129]
	v_mfma_f32_16x16x32_bf16 v[122:125], v[158:161], v[182:185], v[122:125]
	v_mfma_f32_16x16x32_bf16 v[110:113], v[150:153], v[190:193], v[110:113]
	v_mfma_f32_16x16x32_bf16 v[106:109], v[158:161], v[190:193], v[106:109]
	v_mfma_f32_16x16x32_bf16 v[94:97], v[150:153], v[198:201], v[94:97]
	v_mfma_f32_16x16x32_bf16 v[90:93], v[158:161], v[198:201], v[90:93]
	v_mfma_f32_16x16x32_bf16 v[78:81], v[150:153], v[206:209], v[78:81]
	v_mfma_f32_16x16x32_bf16 v[74:77], v[158:161], v[206:209], v[74:77]
	v_mfma_f32_16x16x32_bf16 v[126:129], v[154:157], v[186:189], v[126:129]
	v_mfma_f32_16x16x32_bf16 v[122:125], v[162:165], v[186:189], v[122:125]
	v_mfma_f32_16x16x32_bf16 v[110:113], v[154:157], v[194:197], v[110:113]
	v_mfma_f32_16x16x32_bf16 v[106:109], v[162:165], v[194:197], v[106:109]
	v_mfma_f32_16x16x32_bf16 v[94:97], v[154:157], v[202:205], v[94:97]
	v_mfma_f32_16x16x32_bf16 v[90:93], v[162:165], v[202:205], v[90:93]
	v_mfma_f32_16x16x32_bf16 v[78:81], v[154:157], v[210:213], v[78:81]
	v_mfma_f32_16x16x32_bf16 v[74:77], v[162:165], v[210:213], v[74:77]
	v_mfma_f32_16x16x32_bf16 v[118:121], v[166:169], v[182:185], v[118:121]
	v_mfma_f32_16x16x32_bf16 v[114:117], v[174:177], v[182:185], v[114:117]
	v_mfma_f32_16x16x32_bf16 v[102:105], v[166:169], v[190:193], v[102:105]
	v_mfma_f32_16x16x32_bf16 v[98:101], v[174:177], v[190:193], v[98:101]
	v_mfma_f32_16x16x32_bf16 v[86:89], v[166:169], v[198:201], v[86:89]
	v_mfma_f32_16x16x32_bf16 v[82:85], v[174:177], v[198:201], v[82:85]
	v_mfma_f32_16x16x32_bf16 v[70:73], v[166:169], v[206:209], v[70:73]
	v_mfma_f32_16x16x32_bf16 v[66:69], v[174:177], v[206:209], v[66:69]
	v_mfma_f32_16x16x32_bf16 v[118:121], v[170:173], v[186:189], v[118:121]
	v_mfma_f32_16x16x32_bf16 v[114:117], v[178:181], v[186:189], v[114:117]
	v_mfma_f32_16x16x32_bf16 v[102:105], v[170:173], v[194:197], v[102:105]
	v_mfma_f32_16x16x32_bf16 v[98:101], v[178:181], v[194:197], v[98:101]
	v_mfma_f32_16x16x32_bf16 v[86:89], v[170:173], v[202:205], v[86:89]
	v_mfma_f32_16x16x32_bf16 v[82:85], v[178:181], v[202:205], v[82:85]
	v_mfma_f32_16x16x32_bf16 v[70:73], v[170:173], v[210:213], v[70:73]
	v_mfma_f32_16x16x32_bf16 v[66:69], v[178:181], v[210:213], v[66:69]
	s_barrier
	s_mov_b32 m0, s72
	v_lshl_add_u64 v[144:145], v[144:145], 0, s[4:5]
	ds_read_b128 v[182:185], v149 offset:49152
	ds_read_b128 v[186:189], v149 offset:50176
	ds_read_b128 v[190:193], v149 offset:51200
	ds_read_b128 v[194:197], v149 offset:52224
	ds_read_b128 v[198:201], v149 offset:53248
	ds_read_b128 v[202:205], v149 offset:54272
	ds_read_b128 v[206:209], v149 offset:55296
	ds_read_b128 v[210:213], v149 offset:56320
	global_load_lds_dwordx4 v[144:145], off
	s_add_i32 m0, s72, 0x2000
	s_add_u32 s22, s26, 0x18080
	v_lshl_add_u64 v[144:145], v[214:215], 0, s[4:5]
	s_addc_u32 s23, s27, 0
	s_add_i32 s26, s71, s30
	global_load_lds_dwordx4 v[144:145], off
	v_lshl_add_u64 v[144:145], s[22:23], 0, v[134:135]
	s_mov_b32 m0, s26
	s_nop 0
	global_load_lds_dwordx4 v[144:145], off
	v_lshl_add_u64 v[144:145], s[22:23], 0, v[130:131]
	s_add_i32 m0, s26, 0x2000
	s_nop 0
	global_load_lds_dwordx4 v[144:145], off
	v_lshl_add_u64 v[144:145], v[216:217], 0, s[4:5]
	s_mov_b32 m0, s59
	s_nop 0
	global_load_lds_dwordx4 v[144:145], off
	v_lshl_add_u64 v[144:145], v[218:219], 0, s[4:5]
	s_mov_b32 m0, s60
	s_nop 0
	global_load_lds_dwordx4 v[144:145], off
	s_waitcnt vmcnt(8)
	s_waitcnt lgkmcnt(0)
	s_barrier
	s_waitcnt lgkmcnt(0)
	v_mfma_f32_16x16x32_bf16 v[62:65], v[150:153], v[182:185], v[62:65]
	v_mfma_f32_16x16x32_bf16 v[58:61], v[158:161], v[182:185], v[58:61]
	v_mfma_f32_16x16x32_bf16 v[46:49], v[150:153], v[190:193], v[46:49]
	v_mfma_f32_16x16x32_bf16 v[42:45], v[158:161], v[190:193], v[42:45]
	v_mfma_f32_16x16x32_bf16 v[30:33], v[150:153], v[198:201], v[30:33]
	v_mfma_f32_16x16x32_bf16 v[26:29], v[158:161], v[198:201], v[26:29]
	v_mfma_f32_16x16x32_bf16 v[14:17], v[150:153], v[206:209], v[14:17]
	v_mfma_f32_16x16x32_bf16 v[10:13], v[158:161], v[206:209], v[10:13]
	v_mfma_f32_16x16x32_bf16 v[62:65], v[154:157], v[186:189], v[62:65]
	v_mfma_f32_16x16x32_bf16 v[58:61], v[162:165], v[186:189], v[58:61]
	v_mfma_f32_16x16x32_bf16 v[46:49], v[154:157], v[194:197], v[46:49]
	v_mfma_f32_16x16x32_bf16 v[42:45], v[162:165], v[194:197], v[42:45]
	v_mfma_f32_16x16x32_bf16 v[30:33], v[154:157], v[202:205], v[30:33]
	v_mfma_f32_16x16x32_bf16 v[26:29], v[162:165], v[202:205], v[26:29]
	v_mfma_f32_16x16x32_bf16 v[14:17], v[154:157], v[210:213], v[14:17]
	v_mfma_f32_16x16x32_bf16 v[10:13], v[162:165], v[210:213], v[10:13]
	v_mfma_f32_16x16x32_bf16 v[54:57], v[166:169], v[182:185], v[54:57]
	v_mfma_f32_16x16x32_bf16 v[50:53], v[174:177], v[182:185], v[50:53]
	v_mfma_f32_16x16x32_bf16 v[38:41], v[166:169], v[190:193], v[38:41]
	v_mfma_f32_16x16x32_bf16 v[34:37], v[174:177], v[190:193], v[34:37]
	v_mfma_f32_16x16x32_bf16 v[22:25], v[166:169], v[198:201], v[22:25]
	v_mfma_f32_16x16x32_bf16 v[18:21], v[174:177], v[198:201], v[18:21]
	v_mfma_f32_16x16x32_bf16 v[6:9], v[166:169], v[206:209], v[6:9]
	v_mfma_f32_16x16x32_bf16 v[2:5], v[174:177], v[206:209], v[2:5]
	v_mfma_f32_16x16x32_bf16 v[54:57], v[170:173], v[186:189], v[54:57]
	v_mfma_f32_16x16x32_bf16 v[50:53], v[178:181], v[186:189], v[50:53]
	v_mfma_f32_16x16x32_bf16 v[38:41], v[170:173], v[194:197], v[38:41]
	v_mfma_f32_16x16x32_bf16 v[34:37], v[178:181], v[194:197], v[34:37]
	v_mfma_f32_16x16x32_bf16 v[22:25], v[170:173], v[202:205], v[22:25]
	v_mfma_f32_16x16x32_bf16 v[18:21], v[178:181], v[202:205], v[18:21]
	v_mfma_f32_16x16x32_bf16 v[6:9], v[170:173], v[210:213], v[6:9]
	v_mfma_f32_16x16x32_bf16 v[2:5], v[178:181], v[210:213], v[2:5]
	s_barrier
	s_add_u32 s75, s75, 0x100
	s_addc_u32 s76, s76, 0
	s_cmp_ge_i32 s77, s57
	s_mov_b64 s[22:23], s[24:25]
	s_mov_b32 s26, s77
	s_cbranch_scc0 .LBB0_468

.LBB0_599:
	v_add_u32_e32 v142, s74, v199
	v_add_u32_e32 v162, s75, v199
	ds_read_b128 v[130:133], v142
	ds_read_b128 v[134:137], v142 offset:1024
	ds_read_b128 v[138:141], v142 offset:2048
	ds_read_b128 v[142:145], v142 offset:3072
	ds_read_b128 v[146:149], v162
	ds_read_b128 v[150:153], v162 offset:1024
	ds_read_b128 v[174:177], v162 offset:2048
	ds_read_b128 v[178:181], v162 offset:3072
	s_add_i32 s31, s52, 2
	s_add_u32 s50, s34, 0x3ff000
	s_addc_u32 s51, s35, 0
	s_cmp_eq_u32 s71, s52
	s_cselect_b32 s56, s26, s50
	s_cselect_b32 s57, s27, s51
	s_cselect_b32 s54, s28, s23
	s_cselect_b32 s55, s29, s25
	s_add_u32 s52, s56, 0x400000
	s_addc_u32 s53, s57, 0
	v_lshl_add_u64 v[218:219], s[34:35], 0, v[164:165]
	s_add_i32 m0, s59, 0xc000
	ds_read_b128 v[182:185], v200
	ds_read_b128 v[186:189], v200 offset:1024
	ds_read_b128 v[190:193], v200 offset:2048
	ds_read_b128 v[194:197], v200 offset:3072
	ds_read_b128 v[202:205], v200 offset:4096
	ds_read_b128 v[206:209], v200 offset:5120
	ds_read_b128 v[210:213], v200 offset:6144
	ds_read_b128 v[214:217], v200 offset:7168
	global_load_lds_dwordx4 v[218:219], off
	v_lshl_add_u64 v[218:219], s[34:35], 0, v[166:167]
	s_add_i32 m0, s59, 0xe000
	s_nop 0
	global_load_lds_dwordx4 v[218:219], off
	s_waitcnt vmcnt(8)
	s_waitcnt lgkmcnt(0)
	s_barrier
	s_waitcnt lgkmcnt(0)
	v_mfma_f32_16x16x32_bf16 v[118:121], v[130:133], v[182:185], v[118:121]
	v_mfma_f32_16x16x32_bf16 v[122:125], v[138:141], v[182:185], v[122:125]
	v_mfma_f32_16x16x32_bf16 v[110:113], v[130:133], v[190:193], v[110:113]
	v_mfma_f32_16x16x32_bf16 v[106:109], v[138:141], v[190:193], v[106:109]
	v_mfma_f32_16x16x32_bf16 v[94:97], v[130:133], v[202:205], v[94:97]
	v_mfma_f32_16x16x32_bf16 v[90:93], v[138:141], v[202:205], v[90:93]
	v_mfma_f32_16x16x32_bf16 v[78:81], v[130:133], v[210:213], v[78:81]
	v_mfma_f32_16x16x32_bf16 v[74:77], v[138:141], v[210:213], v[74:77]
	v_mfma_f32_16x16x32_bf16 v[118:121], v[134:137], v[186:189], v[118:121]
	v_mfma_f32_16x16x32_bf16 v[122:125], v[142:145], v[186:189], v[122:125]
	v_mfma_f32_16x16x32_bf16 v[110:113], v[134:137], v[194:197], v[110:113]
	v_mfma_f32_16x16x32_bf16 v[106:109], v[142:145], v[194:197], v[106:109]
	v_mfma_f32_16x16x32_bf16 v[94:97], v[134:137], v[206:209], v[94:97]
	v_mfma_f32_16x16x32_bf16 v[90:93], v[142:145], v[206:209], v[90:93]
	v_mfma_f32_16x16x32_bf16 v[78:81], v[134:137], v[214:217], v[78:81]
	v_mfma_f32_16x16x32_bf16 v[74:77], v[142:145], v[214:217], v[74:77]
	v_mfma_f32_16x16x32_bf16 v[126:129], v[146:149], v[182:185], v[126:129]
	v_mfma_f32_16x16x32_bf16 v[114:117], v[174:177], v[182:185], v[114:117]
	v_mfma_f32_16x16x32_bf16 v[102:105], v[146:149], v[190:193], v[102:105]
	v_mfma_f32_16x16x32_bf16 v[98:101], v[174:177], v[190:193], v[98:101]
	v_mfma_f32_16x16x32_bf16 v[86:89], v[146:149], v[202:205], v[86:89]
	v_mfma_f32_16x16x32_bf16 v[82:85], v[174:177], v[202:205], v[82:85]
	v_mfma_f32_16x16x32_bf16 v[70:73], v[146:149], v[210:213], v[70:73]
	v_mfma_f32_16x16x32_bf16 v[66:69], v[174:177], v[210:213], v[66:69]
	v_mfma_f32_16x16x32_bf16 v[126:129], v[150:153], v[186:189], v[126:129]
	v_mfma_f32_16x16x32_bf16 v[114:117], v[178:181], v[186:189], v[114:117]
	v_mfma_f32_16x16x32_bf16 v[102:105], v[150:153], v[194:197], v[102:105]
	v_mfma_f32_16x16x32_bf16 v[98:101], v[178:181], v[194:197], v[98:101]
	v_mfma_f32_16x16x32_bf16 v[86:89], v[150:153], v[206:209], v[86:89]
	v_mfma_f32_16x16x32_bf16 v[82:85], v[178:181], v[206:209], v[82:85]
	v_mfma_f32_16x16x32_bf16 v[70:73], v[150:153], v[214:217], v[70:73]
	v_mfma_f32_16x16x32_bf16 v[66:69], v[178:181], v[214:217], v[66:69]
	s_barrier
	s_add_i32 s50, s74, s41
	v_lshl_add_u64 v[218:219], s[54:55], 0, v[156:157]
	s_mov_b32 m0, s50
	ds_read_b128 v[182:185], v200 offset:16384
	ds_read_b128 v[186:189], v200 offset:17408
	ds_read_b128 v[190:193], v200 offset:18432
	ds_read_b128 v[194:197], v200 offset:19456
	ds_read_b128 v[202:205], v200 offset:20480
	ds_read_b128 v[206:209], v200 offset:21504
	ds_read_b128 v[210:213], v200 offset:22528
	ds_read_b128 v[214:217], v200 offset:23552
	global_load_lds_dwordx4 v[218:219], off
	s_add_i32 m0, s50, 0x2000
	s_add_u32 s50, s54, 0x20000
	v_lshl_add_u64 v[220:221], s[54:55], 0, v[160:161]
	s_addc_u32 s51, s55, 0
	s_add_i32 s78, s75, s41
	global_load_lds_dwordx4 v[220:221], off
	v_lshl_add_u64 v[222:223], s[50:51], 0, v[156:157]
	s_mov_b32 m0, s78
	s_nop 0
	global_load_lds_dwordx4 v[222:223], off
	v_lshl_add_u64 v[222:223], s[50:51], 0, v[160:161]
	s_add_i32 m0, s78, 0x2000
	s_nop 0
	global_load_lds_dwordx4 v[222:223], off
	v_lshl_add_u64 v[222:223], s[56:57], 0, v[154:155]
	s_mov_b32 m0, s59
	s_nop 0
	global_load_lds_dwordx4 v[222:223], off
	v_lshl_add_u64 v[222:223], s[56:57], 0, v[158:159]
	s_mov_b32 m0, s60
	s_nop 0
	global_load_lds_dwordx4 v[222:223], off
	s_waitcnt vmcnt(8)
	s_waitcnt lgkmcnt(0)
	s_barrier
	s_waitcnt lgkmcnt(0)
	v_mfma_f32_16x16x32_bf16 v[62:65], v[130:133], v[182:185], v[62:65]
	v_mfma_f32_16x16x32_bf16 v[58:61], v[138:141], v[182:185], v[58:61]
	v_mfma_f32_16x16x32_bf16 v[46:49], v[130:133], v[190:193], v[46:49]
	v_mfma_f32_16x16x32_bf16 v[42:45], v[138:141], v[190:193], v[42:45]
	v_mfma_f32_16x16x32_bf16 v[30:33], v[130:133], v[202:205], v[30:33]
	v_mfma_f32_16x16x32_bf16 v[26:29], v[138:141], v[202:205], v[26:29]
	v_mfma_f32_16x16x32_bf16 v[14:17], v[130:133], v[210:213], v[14:17]
	v_mfma_f32_16x16x32_bf16 v[10:13], v[138:141], v[210:213], v[10:13]
	v_mfma_f32_16x16x32_bf16 v[62:65], v[134:137], v[186:189], v[62:65]
	v_mfma_f32_16x16x32_bf16 v[58:61], v[142:145], v[186:189], v[58:61]
	v_mfma_f32_16x16x32_bf16 v[46:49], v[134:137], v[194:197], v[46:49]
	v_mfma_f32_16x16x32_bf16 v[42:45], v[142:145], v[194:197], v[42:45]
	v_mfma_f32_16x16x32_bf16 v[30:33], v[134:137], v[206:209], v[30:33]
	v_mfma_f32_16x16x32_bf16 v[26:29], v[142:145], v[206:209], v[26:29]
	v_mfma_f32_16x16x32_bf16 v[14:17], v[134:137], v[214:217], v[14:17]
	v_mfma_f32_16x16x32_bf16 v[10:13], v[142:145], v[214:217], v[10:13]
	v_mfma_f32_16x16x32_bf16 v[54:57], v[146:149], v[182:185], v[54:57]
	v_mfma_f32_16x16x32_bf16 v[50:53], v[174:177], v[182:185], v[50:53]
	v_mfma_f32_16x16x32_bf16 v[38:41], v[146:149], v[190:193], v[38:41]
	v_mfma_f32_16x16x32_bf16 v[34:37], v[174:177], v[190:193], v[34:37]
	v_mfma_f32_16x16x32_bf16 v[22:25], v[146:149], v[202:205], v[22:25]
	v_mfma_f32_16x16x32_bf16 v[18:21], v[174:177], v[202:205], v[18:21]
	v_mfma_f32_16x16x32_bf16 v[6:9], v[146:149], v[210:213], v[6:9]
	v_mfma_f32_16x16x32_bf16 v[2:5], v[174:177], v[210:213], v[2:5]
	v_mfma_f32_16x16x32_bf16 v[54:57], v[150:153], v[186:189], v[54:57]
	v_mfma_f32_16x16x32_bf16 v[50:53], v[178:181], v[186:189], v[50:53]
	v_mfma_f32_16x16x32_bf16 v[38:41], v[150:153], v[194:197], v[38:41]
	v_mfma_f32_16x16x32_bf16 v[34:37], v[178:181], v[194:197], v[34:37]
	v_mfma_f32_16x16x32_bf16 v[22:25], v[150:153], v[206:209], v[22:25]
	v_mfma_f32_16x16x32_bf16 v[18:21], v[178:181], v[206:209], v[18:21]
	v_mfma_f32_16x16x32_bf16 v[6:9], v[150:153], v[214:217], v[6:9]
	v_mfma_f32_16x16x32_bf16 v[2:5], v[178:181], v[214:217], v[2:5]
	s_barrier
	s_add_i32 s78, 0, 0x18000
	s_add_i32 s79, 0, 0x1c000
	v_add_u32_e32 v142, s78, v199
	v_add_u32_e32 v162, s79, v199
	ds_read_b128 v[130:133], v142
	ds_read_b128 v[134:137], v142 offset:1024
	ds_read_b128 v[138:141], v142 offset:2048
	ds_read_b128 v[142:145], v142 offset:3072
	ds_read_b128 v[146:149], v162
	ds_read_b128 v[150:153], v162 offset:1024
	ds_read_b128 v[174:177], v162 offset:2048
	ds_read_b128 v[178:181], v162 offset:3072
	s_add_u32 s50, s56, 0x1000
	s_addc_u32 s51, s57, 0
	s_mov_b32 m0, s61
	v_lshl_add_u64 v[222:223], s[50:51], 0, v[154:155]
	ds_read_b128 v[182:185], v200 offset:32768
	ds_read_b128 v[186:189], v200 offset:33792
	ds_read_b128 v[190:193], v200 offset:34816
	ds_read_b128 v[194:197], v200 offset:35840
	ds_read_b128 v[202:205], v200 offset:36864
	ds_read_b128 v[206:209], v200 offset:37888
	ds_read_b128 v[210:213], v200 offset:38912
	ds_read_b128 v[214:217], v200 offset:39936
	global_load_lds_dwordx4 v[222:223], off
	v_lshl_add_u64 v[222:223], s[50:51], 0, v[158:159]
	s_mov_b32 m0, s62
	s_nop 0
	global_load_lds_dwordx4 v[222:223], off
	s_waitcnt vmcnt(8)
	s_waitcnt lgkmcnt(0)
	s_barrier
	s_waitcnt lgkmcnt(0)
	v_mfma_f32_16x16x32_bf16 v[118:121], v[130:133], v[182:185], v[118:121]
	v_mfma_f32_16x16x32_bf16 v[122:125], v[138:141], v[182:185], v[122:125]
	v_mfma_f32_16x16x32_bf16 v[110:113], v[130:133], v[190:193], v[110:113]
	v_mfma_f32_16x16x32_bf16 v[106:109], v[138:141], v[190:193], v[106:109]
	v_mfma_f32_16x16x32_bf16 v[94:97], v[130:133], v[202:205], v[94:97]
	v_mfma_f32_16x16x32_bf16 v[90:93], v[138:141], v[202:205], v[90:93]
	v_mfma_f32_16x16x32_bf16 v[78:81], v[130:133], v[210:213], v[78:81]
	v_mfma_f32_16x16x32_bf16 v[74:77], v[138:141], v[210:213], v[74:77]
	v_mfma_f32_16x16x32_bf16 v[118:121], v[134:137], v[186:189], v[118:121]
	v_mfma_f32_16x16x32_bf16 v[122:125], v[142:145], v[186:189], v[122:125]
	v_mfma_f32_16x16x32_bf16 v[110:113], v[134:137], v[194:197], v[110:113]
	v_mfma_f32_16x16x32_bf16 v[106:109], v[142:145], v[194:197], v[106:109]
	v_mfma_f32_16x16x32_bf16 v[94:97], v[134:137], v[206:209], v[94:97]
	v_mfma_f32_16x16x32_bf16 v[90:93], v[142:145], v[206:209], v[90:93]
	v_mfma_f32_16x16x32_bf16 v[78:81], v[134:137], v[214:217], v[78:81]
	v_mfma_f32_16x16x32_bf16 v[74:77], v[142:145], v[214:217], v[74:77]
	v_mfma_f32_16x16x32_bf16 v[126:129], v[146:149], v[182:185], v[126:129]
	v_mfma_f32_16x16x32_bf16 v[114:117], v[174:177], v[182:185], v[114:117]
	v_mfma_f32_16x16x32_bf16 v[102:105], v[146:149], v[190:193], v[102:105]
	v_mfma_f32_16x16x32_bf16 v[98:101], v[174:177], v[190:193], v[98:101]
	v_mfma_f32_16x16x32_bf16 v[86:89], v[146:149], v[202:205], v[86:89]
	v_mfma_f32_16x16x32_bf16 v[82:85], v[174:177], v[202:205], v[82:85]
	v_mfma_f32_16x16x32_bf16 v[70:73], v[146:149], v[210:213], v[70:73]
	v_mfma_f32_16x16x32_bf16 v[66:69], v[174:177], v[210:213], v[66:69]
	v_mfma_f32_16x16x32_bf16 v[126:129], v[150:153], v[186:189], v[126:129]
	v_mfma_f32_16x16x32_bf16 v[114:117], v[178:181], v[186:189], v[114:117]
	v_mfma_f32_16x16x32_bf16 v[102:105], v[150:153], v[194:197], v[102:105]
	v_mfma_f32_16x16x32_bf16 v[98:101], v[178:181], v[194:197], v[98:101]
	v_mfma_f32_16x16x32_bf16 v[86:89], v[150:153], v[206:209], v[86:89]
	v_mfma_f32_16x16x32_bf16 v[82:85], v[178:181], v[206:209], v[82:85]
	v_mfma_f32_16x16x32_bf16 v[70:73], v[150:153], v[214:217], v[70:73]
	v_mfma_f32_16x16x32_bf16 v[66:69], v[178:181], v[214:217], v[66:69]
	s_barrier
	s_add_i32 s50, s78, s41
	v_lshl_add_u64 v[218:219], v[218:219], 0, s[14:15]
	s_mov_b32 m0, s50
	ds_read_b128 v[182:185], v200 offset:49152
	ds_read_b128 v[186:189], v200 offset:50176
	ds_read_b128 v[190:193], v200 offset:51200
	ds_read_b128 v[194:197], v200 offset:52224
	ds_read_b128 v[202:205], v200 offset:53248
	ds_read_b128 v[206:209], v200 offset:54272
	ds_read_b128 v[210:213], v200 offset:55296
	ds_read_b128 v[214:217], v200 offset:56320
	global_load_lds_dwordx4 v[218:219], off
	s_add_i32 m0, s50, 0x2000
	s_add_u32 s50, s54, 0x20080
	v_lshl_add_u64 v[218:219], v[220:221], 0, s[14:15]
	s_addc_u32 s51, s55, 0
	s_add_i32 s54, s79, s41
	global_load_lds_dwordx4 v[218:219], off
	v_lshl_add_u64 v[218:219], s[50:51], 0, v[156:157]
	s_mov_b32 m0, s54
	s_nop 0
	global_load_lds_dwordx4 v[218:219], off
	v_lshl_add_u64 v[218:219], s[50:51], 0, v[160:161]
	s_add_i32 m0, s54, 0x2000
	s_nop 0
	global_load_lds_dwordx4 v[218:219], off
	v_lshl_add_u64 v[218:219], s[52:53], 0, v[154:155]
	s_mov_b32 m0, s69
	s_nop 0
	global_load_lds_dwordx4 v[218:219], off
	v_lshl_add_u64 v[218:219], s[52:53], 0, v[158:159]
	s_mov_b32 m0, s70
	s_nop 0
	global_load_lds_dwordx4 v[218:219], off
	s_waitcnt vmcnt(8)
	s_waitcnt lgkmcnt(0)
	s_barrier
	s_waitcnt lgkmcnt(0)
	v_mfma_f32_16x16x32_bf16 v[62:65], v[130:133], v[182:185], v[62:65]
	v_mfma_f32_16x16x32_bf16 v[58:61], v[138:141], v[182:185], v[58:61]
	v_mfma_f32_16x16x32_bf16 v[46:49], v[130:133], v[190:193], v[46:49]
	v_mfma_f32_16x16x32_bf16 v[42:45], v[138:141], v[190:193], v[42:45]
	v_mfma_f32_16x16x32_bf16 v[30:33], v[130:133], v[202:205], v[30:33]
	v_mfma_f32_16x16x32_bf16 v[26:29], v[138:141], v[202:205], v[26:29]
	v_mfma_f32_16x16x32_bf16 v[14:17], v[130:133], v[210:213], v[14:17]
	v_mfma_f32_16x16x32_bf16 v[10:13], v[138:141], v[210:213], v[10:13]
	v_mfma_f32_16x16x32_bf16 v[62:65], v[134:137], v[186:189], v[62:65]
	v_mfma_f32_16x16x32_bf16 v[58:61], v[142:145], v[186:189], v[58:61]
	v_mfma_f32_16x16x32_bf16 v[46:49], v[134:137], v[194:197], v[46:49]
	v_mfma_f32_16x16x32_bf16 v[42:45], v[142:145], v[194:197], v[42:45]
	v_mfma_f32_16x16x32_bf16 v[30:33], v[134:137], v[206:209], v[30:33]
	v_mfma_f32_16x16x32_bf16 v[26:29], v[142:145], v[206:209], v[26:29]
	v_mfma_f32_16x16x32_bf16 v[14:17], v[134:137], v[214:217], v[14:17]
	v_mfma_f32_16x16x32_bf16 v[10:13], v[142:145], v[214:217], v[10:13]
	v_mfma_f32_16x16x32_bf16 v[54:57], v[146:149], v[182:185], v[54:57]
	v_mfma_f32_16x16x32_bf16 v[50:53], v[174:177], v[182:185], v[50:53]
	v_mfma_f32_16x16x32_bf16 v[38:41], v[146:149], v[190:193], v[38:41]
	v_mfma_f32_16x16x32_bf16 v[34:37], v[174:177], v[190:193], v[34:37]
	v_mfma_f32_16x16x32_bf16 v[22:25], v[146:149], v[202:205], v[22:25]
	v_mfma_f32_16x16x32_bf16 v[18:21], v[174:177], v[202:205], v[18:21]
	v_mfma_f32_16x16x32_bf16 v[6:9], v[146:149], v[210:213], v[6:9]
	v_mfma_f32_16x16x32_bf16 v[2:5], v[174:177], v[210:213], v[2:5]
	v_mfma_f32_16x16x32_bf16 v[54:57], v[150:153], v[186:189], v[54:57]
	v_mfma_f32_16x16x32_bf16 v[50:53], v[178:181], v[186:189], v[50:53]
	v_mfma_f32_16x16x32_bf16 v[38:41], v[150:153], v[194:197], v[38:41]
	v_mfma_f32_16x16x32_bf16 v[34:37], v[178:181], v[194:197], v[34:37]
	v_mfma_f32_16x16x32_bf16 v[22:25], v[150:153], v[206:209], v[22:25]
	v_mfma_f32_16x16x32_bf16 v[18:21], v[178:181], v[206:209], v[18:21]
	v_mfma_f32_16x16x32_bf16 v[6:9], v[150:153], v[214:217], v[6:9]
	v_mfma_f32_16x16x32_bf16 v[2:5], v[178:181], v[214:217], v[2:5]
	s_barrier
	s_add_u32 s23, s23, 0x100
	s_addc_u32 s25, s25, 0
	s_add_u32 s34, s34, 0x800000
	s_addc_u32 s35, s35, 0
	s_cmp_ge_i32 s31, s67
	s_mov_b32 s52, s31
	s_cbranch_scc0 .LBB0_599

.LBB0_740:
	v_add_u32_e32 v144, s88, v188
	v_add_u32_e32 v160, s89, v188
	ds_read_b128 v[132:135], v144
	ds_read_b128 v[136:139], v144 offset:1024
	ds_read_b128 v[140:143], v144 offset:2048
	ds_read_b128 v[144:147], v144 offset:3072
	ds_read_b128 v[148:151], v160
	ds_read_b128 v[152:155], v160 offset:1024
	ds_read_b128 v[156:159], v160 offset:2048
	ds_read_b128 v[184:187], v160 offset:3072
	s_add_i32 s92, s55, 2
	s_add_u32 s50, s60, 0x3fc000
	s_addc_u32 s51, s61, 0
	s_cmp_eq_u32 s87, s55
	s_cselect_b32 s70, s64, s50
	s_cselect_b32 s71, s65, s51
	s_cselect_b32 s69, s67, s53
	s_cselect_b32 s68, s66, s13
	s_add_u32 s62, s70, 0x400000
	s_addc_u32 s63, s71, 0
	v_lshl_add_u64 v[160:161], s[60:61], 0, v[176:177]
	s_add_i32 m0, s77, 0xc000
	ds_read_b128 v[192:195], v189
	ds_read_b128 v[196:199], v189 offset:1024
	ds_read_b128 v[200:203], v189 offset:2048
	ds_read_b128 v[204:207], v189 offset:3072
	ds_read_b128 v[208:211], v189 offset:4096
	ds_read_b128 v[212:215], v189 offset:5120
	ds_read_b128 v[216:219], v189 offset:6144
	ds_read_b128 v[220:223], v189 offset:7168
	global_load_lds_dwordx4 v[160:161], off
	v_lshl_add_u64 v[160:161], s[60:61], 0, v[178:179]
	s_add_i32 m0, s77, 0xe000
	s_nop 0
	global_load_lds_dwordx4 v[160:161], off
	s_waitcnt vmcnt(8)
	s_waitcnt lgkmcnt(0)
	s_barrier
	s_waitcnt lgkmcnt(0)
	v_mfma_f32_16x16x32_bf16 v[30:33], v[132:135], v[192:195], v[30:33]
	v_mfma_f32_16x16x32_bf16 v[26:29], v[140:143], v[192:195], v[26:29]
	v_mfma_f32_16x16x32_bf16 v[86:89], v[132:135], v[200:203], v[86:89]
	v_mfma_f32_16x16x32_bf16 v[66:69], v[140:143], v[200:203], v[66:69]
	v_mfma_f32_16x16x32_bf16 v[94:97], v[132:135], v[208:211], v[94:97]
	v_mfma_f32_16x16x32_bf16 v[82:85], v[140:143], v[208:211], v[82:85]
	v_mfma_f32_16x16x32_bf16 v[90:93], v[132:135], v[216:219], v[90:93]
	v_mfma_f32_16x16x32_bf16 v[78:81], v[140:143], v[216:219], v[78:81]
	v_mfma_f32_16x16x32_bf16 v[30:33], v[136:139], v[196:199], v[30:33]
	v_mfma_f32_16x16x32_bf16 v[26:29], v[144:147], v[196:199], v[26:29]
	v_mfma_f32_16x16x32_bf16 v[86:89], v[136:139], v[204:207], v[86:89]
	v_mfma_f32_16x16x32_bf16 v[66:69], v[144:147], v[204:207], v[66:69]
	v_mfma_f32_16x16x32_bf16 v[94:97], v[136:139], v[212:215], v[94:97]
	v_mfma_f32_16x16x32_bf16 v[82:85], v[144:147], v[212:215], v[82:85]
	v_mfma_f32_16x16x32_bf16 v[90:93], v[136:139], v[220:223], v[90:93]
	v_mfma_f32_16x16x32_bf16 v[78:81], v[144:147], v[220:223], v[78:81]
	v_mfma_f32_16x16x32_bf16 v[50:53], v[148:151], v[192:195], v[50:53]
	v_mfma_f32_16x16x32_bf16 v[42:45], v[156:159], v[192:195], v[42:45]
	v_mfma_f32_16x16x32_bf16 v[14:17], v[148:151], v[200:203], v[14:17]
	v_mfma_f32_16x16x32_bf16 v[2:5], v[156:159], v[200:203], v[2:5]
	v_mfma_f32_16x16x32_bf16 v[22:25], v[148:151], v[208:211], v[22:25]
	v_mfma_f32_16x16x32_bf16 v[10:13], v[156:159], v[208:211], v[10:13]
	v_mfma_f32_16x16x32_bf16 v[18:21], v[148:151], v[216:219], v[18:21]
	v_mfma_f32_16x16x32_bf16 v[6:9], v[156:159], v[216:219], v[6:9]
	v_mfma_f32_16x16x32_bf16 v[50:53], v[152:155], v[196:199], v[50:53]
	v_mfma_f32_16x16x32_bf16 v[42:45], v[184:187], v[196:199], v[42:45]
	v_mfma_f32_16x16x32_bf16 v[14:17], v[152:155], v[204:207], v[14:17]
	v_mfma_f32_16x16x32_bf16 v[2:5], v[184:187], v[204:207], v[2:5]
	v_mfma_f32_16x16x32_bf16 v[22:25], v[152:155], v[212:215], v[22:25]
	v_mfma_f32_16x16x32_bf16 v[10:13], v[184:187], v[212:215], v[10:13]
	v_mfma_f32_16x16x32_bf16 v[18:21], v[152:155], v[220:223], v[18:21]
	v_mfma_f32_16x16x32_bf16 v[6:9], v[184:187], v[220:223], v[6:9]
	s_barrier
	s_add_i32 s50, s88, s76
	v_lshl_add_u64 v[160:161], s[68:69], 0, v[164:165]
	s_mov_b32 m0, s50
	ds_read_b128 v[192:195], v189 offset:16384
	ds_read_b128 v[196:199], v189 offset:17408
	ds_read_b128 v[200:203], v189 offset:18432
	ds_read_b128 v[204:207], v189 offset:19456
	ds_read_b128 v[208:211], v189 offset:20480
	ds_read_b128 v[212:215], v189 offset:21504
	ds_read_b128 v[216:219], v189 offset:22528
	ds_read_b128 v[220:223], v189 offset:23552
	global_load_lds_dwordx4 v[160:161], off
	s_add_i32 m0, s50, 0x2000
	s_add_u32 s50, s68, 0x10000
	v_lshl_add_u64 v[224:225], s[68:69], 0, v[168:169]
	s_addc_u32 s51, s69, 0
	s_add_i32 s55, s89, s76
	global_load_lds_dwordx4 v[224:225], off
	v_lshl_add_u64 v[226:227], s[50:51], 0, v[164:165]
	s_mov_b32 m0, s55
	s_nop 0
	global_load_lds_dwordx4 v[226:227], off
	v_lshl_add_u64 v[226:227], s[50:51], 0, v[168:169]
	s_add_i32 m0, s55, 0x2000
	s_nop 0
	global_load_lds_dwordx4 v[226:227], off
	v_lshl_add_u64 v[226:227], s[70:71], 0, v[162:163]
	s_mov_b32 m0, s77
	s_nop 0
	global_load_lds_dwordx4 v[226:227], off
	v_lshl_add_u64 v[226:227], s[70:71], 0, v[166:167]
	s_mov_b32 m0, s78
	s_nop 0
	global_load_lds_dwordx4 v[226:227], off
	s_waitcnt vmcnt(8)
	s_waitcnt lgkmcnt(0)
	s_barrier
	s_waitcnt lgkmcnt(0)
	v_mfma_f32_16x16x32_bf16 v[118:121], v[132:135], v[192:195], v[118:121]
	v_mfma_f32_16x16x32_bf16 v[102:105], v[140:143], v[192:195], v[102:105]
	v_mfma_f32_16x16x32_bf16 v[114:117], v[132:135], v[200:203], v[114:117]
	v_mfma_f32_16x16x32_bf16 v[98:101], v[140:143], v[200:203], v[98:101]
	v_mfma_f32_16x16x32_bf16 v[126:129], v[132:135], v[208:211], v[126:129]
	v_mfma_f32_16x16x32_bf16 v[110:113], v[140:143], v[208:211], v[110:113]
	v_mfma_f32_16x16x32_bf16 v[122:125], v[132:135], v[216:219], v[122:125]
	v_mfma_f32_16x16x32_bf16 v[106:109], v[140:143], v[216:219], v[106:109]
	v_mfma_f32_16x16x32_bf16 v[118:121], v[136:139], v[196:199], v[118:121]
	v_mfma_f32_16x16x32_bf16 v[102:105], v[144:147], v[196:199], v[102:105]
	v_mfma_f32_16x16x32_bf16 v[114:117], v[136:139], v[204:207], v[114:117]
	v_mfma_f32_16x16x32_bf16 v[98:101], v[144:147], v[204:207], v[98:101]
	v_mfma_f32_16x16x32_bf16 v[126:129], v[136:139], v[212:215], v[126:129]
	v_mfma_f32_16x16x32_bf16 v[110:113], v[144:147], v[212:215], v[110:113]
	v_mfma_f32_16x16x32_bf16 v[122:125], v[136:139], v[220:223], v[122:125]
	v_mfma_f32_16x16x32_bf16 v[106:109], v[144:147], v[220:223], v[106:109]
	v_mfma_f32_16x16x32_bf16 v[62:65], v[148:151], v[192:195], v[62:65]
	v_mfma_f32_16x16x32_bf16 v[38:41], v[156:159], v[192:195], v[38:41]
	v_mfma_f32_16x16x32_bf16 v[58:61], v[148:151], v[200:203], v[58:61]
	v_mfma_f32_16x16x32_bf16 v[34:37], v[156:159], v[200:203], v[34:37]
	v_mfma_f32_16x16x32_bf16 v[74:77], v[148:151], v[208:211], v[74:77]
	v_mfma_f32_16x16x32_bf16 v[54:57], v[156:159], v[208:211], v[54:57]
	v_mfma_f32_16x16x32_bf16 v[70:73], v[148:151], v[216:219], v[70:73]
	v_mfma_f32_16x16x32_bf16 v[46:49], v[156:159], v[216:219], v[46:49]
	v_mfma_f32_16x16x32_bf16 v[62:65], v[152:155], v[196:199], v[62:65]
	v_mfma_f32_16x16x32_bf16 v[38:41], v[184:187], v[196:199], v[38:41]
	v_mfma_f32_16x16x32_bf16 v[58:61], v[152:155], v[204:207], v[58:61]
	v_mfma_f32_16x16x32_bf16 v[34:37], v[184:187], v[204:207], v[34:37]
	v_mfma_f32_16x16x32_bf16 v[74:77], v[152:155], v[212:215], v[74:77]
	v_mfma_f32_16x16x32_bf16 v[54:57], v[184:187], v[212:215], v[54:57]
	v_mfma_f32_16x16x32_bf16 v[70:73], v[152:155], v[220:223], v[70:73]
	v_mfma_f32_16x16x32_bf16 v[46:49], v[184:187], v[220:223], v[46:49]
	s_barrier
	s_add_i32 s55, 0, 0x18000
	s_add_i32 s93, 0, 0x1c000
	v_add_u32_e32 v144, s55, v188
	v_add_u32_e32 v184, s93, v188
	ds_read_b128 v[132:135], v144
	ds_read_b128 v[136:139], v144 offset:1024
	ds_read_b128 v[140:143], v144 offset:2048
	ds_read_b128 v[144:147], v144 offset:3072
	ds_read_b128 v[148:151], v184
	ds_read_b128 v[152:155], v184 offset:1024
	ds_read_b128 v[156:159], v184 offset:2048
	ds_read_b128 v[184:187], v184 offset:3072
	s_add_u32 s50, s70, 0x4000
	s_addc_u32 s51, s71, 0
	s_mov_b32 m0, s79
	v_lshl_add_u64 v[226:227], s[50:51], 0, v[162:163]
	ds_read_b128 v[192:195], v189 offset:32768
	ds_read_b128 v[196:199], v189 offset:33792
	ds_read_b128 v[200:203], v189 offset:34816
	ds_read_b128 v[204:207], v189 offset:35840
	ds_read_b128 v[208:211], v189 offset:36864
	ds_read_b128 v[212:215], v189 offset:37888
	ds_read_b128 v[216:219], v189 offset:38912
	ds_read_b128 v[220:223], v189 offset:39936
	global_load_lds_dwordx4 v[226:227], off
	v_lshl_add_u64 v[226:227], s[50:51], 0, v[166:167]
	s_mov_b32 m0, s80
	s_nop 0
	global_load_lds_dwordx4 v[226:227], off
	s_waitcnt vmcnt(8)
	s_waitcnt lgkmcnt(0)
	s_barrier
	s_waitcnt lgkmcnt(0)
	v_mfma_f32_16x16x32_bf16 v[30:33], v[132:135], v[192:195], v[30:33]
	v_mfma_f32_16x16x32_bf16 v[26:29], v[140:143], v[192:195], v[26:29]
	v_mfma_f32_16x16x32_bf16 v[86:89], v[132:135], v[200:203], v[86:89]
	v_mfma_f32_16x16x32_bf16 v[66:69], v[140:143], v[200:203], v[66:69]
	v_mfma_f32_16x16x32_bf16 v[94:97], v[132:135], v[208:211], v[94:97]
	v_mfma_f32_16x16x32_bf16 v[82:85], v[140:143], v[208:211], v[82:85]
	v_mfma_f32_16x16x32_bf16 v[90:93], v[132:135], v[216:219], v[90:93]
	v_mfma_f32_16x16x32_bf16 v[78:81], v[140:143], v[216:219], v[78:81]
	v_mfma_f32_16x16x32_bf16 v[30:33], v[136:139], v[196:199], v[30:33]
	v_mfma_f32_16x16x32_bf16 v[26:29], v[144:147], v[196:199], v[26:29]
	v_mfma_f32_16x16x32_bf16 v[86:89], v[136:139], v[204:207], v[86:89]
	v_mfma_f32_16x16x32_bf16 v[66:69], v[144:147], v[204:207], v[66:69]
	v_mfma_f32_16x16x32_bf16 v[94:97], v[136:139], v[212:215], v[94:97]
	v_mfma_f32_16x16x32_bf16 v[82:85], v[144:147], v[212:215], v[82:85]
	v_mfma_f32_16x16x32_bf16 v[90:93], v[136:139], v[220:223], v[90:93]
	v_mfma_f32_16x16x32_bf16 v[78:81], v[144:147], v[220:223], v[78:81]
	v_mfma_f32_16x16x32_bf16 v[50:53], v[148:151], v[192:195], v[50:53]
	v_mfma_f32_16x16x32_bf16 v[42:45], v[156:159], v[192:195], v[42:45]
	v_mfma_f32_16x16x32_bf16 v[14:17], v[148:151], v[200:203], v[14:17]
	v_mfma_f32_16x16x32_bf16 v[2:5], v[156:159], v[200:203], v[2:5]
	v_mfma_f32_16x16x32_bf16 v[22:25], v[148:151], v[208:211], v[22:25]
	v_mfma_f32_16x16x32_bf16 v[10:13], v[156:159], v[208:211], v[10:13]
	v_mfma_f32_16x16x32_bf16 v[18:21], v[148:151], v[216:219], v[18:21]
	v_mfma_f32_16x16x32_bf16 v[6:9], v[156:159], v[216:219], v[6:9]
	v_mfma_f32_16x16x32_bf16 v[50:53], v[152:155], v[196:199], v[50:53]
	v_mfma_f32_16x16x32_bf16 v[42:45], v[184:187], v[196:199], v[42:45]
	v_mfma_f32_16x16x32_bf16 v[14:17], v[152:155], v[204:207], v[14:17]
	v_mfma_f32_16x16x32_bf16 v[2:5], v[184:187], v[204:207], v[2:5]
	v_mfma_f32_16x16x32_bf16 v[22:25], v[152:155], v[212:215], v[22:25]
	v_mfma_f32_16x16x32_bf16 v[10:13], v[184:187], v[212:215], v[10:13]
	v_mfma_f32_16x16x32_bf16 v[18:21], v[152:155], v[220:223], v[18:21]
	v_mfma_f32_16x16x32_bf16 v[6:9], v[184:187], v[220:223], v[6:9]
	s_barrier
	s_add_i32 s50, s55, s76
	v_lshl_add_u64 v[160:161], v[160:161], 0, s[14:15]
	s_mov_b32 m0, s50
	ds_read_b128 v[192:195], v189 offset:49152
	ds_read_b128 v[196:199], v189 offset:50176
	ds_read_b128 v[200:203], v189 offset:51200
	ds_read_b128 v[204:207], v189 offset:52224
	ds_read_b128 v[208:211], v189 offset:53248
	ds_read_b128 v[212:215], v189 offset:54272
	ds_read_b128 v[216:219], v189 offset:55296
	ds_read_b128 v[220:223], v189 offset:56320
	global_load_lds_dwordx4 v[160:161], off
	s_add_i32 m0, s50, 0x2000
	s_add_u32 s50, s68, 0x10080
	v_lshl_add_u64 v[160:161], v[224:225], 0, s[14:15]
	s_addc_u32 s51, s69, 0
	s_add_i32 s55, s93, s76
	global_load_lds_dwordx4 v[160:161], off
	v_lshl_add_u64 v[160:161], s[50:51], 0, v[164:165]
	s_mov_b32 m0, s55
	s_nop 0
	global_load_lds_dwordx4 v[160:161], off
	v_lshl_add_u64 v[160:161], s[50:51], 0, v[168:169]
	s_add_i32 m0, s55, 0x2000
	s_nop 0
	global_load_lds_dwordx4 v[160:161], off
	v_lshl_add_u64 v[160:161], s[62:63], 0, v[162:163]
	s_mov_b32 m0, s84
	s_nop 0
	global_load_lds_dwordx4 v[160:161], off
	v_lshl_add_u64 v[160:161], s[62:63], 0, v[166:167]
	s_mov_b32 m0, s85
	s_nop 0
	global_load_lds_dwordx4 v[160:161], off
	s_waitcnt vmcnt(8)
	s_waitcnt lgkmcnt(0)
	s_barrier
	s_waitcnt lgkmcnt(0)
	v_mfma_f32_16x16x32_bf16 v[118:121], v[132:135], v[192:195], v[118:121]
	v_mfma_f32_16x16x32_bf16 v[102:105], v[140:143], v[192:195], v[102:105]
	v_mfma_f32_16x16x32_bf16 v[114:117], v[132:135], v[200:203], v[114:117]
	v_mfma_f32_16x16x32_bf16 v[98:101], v[140:143], v[200:203], v[98:101]
	v_mfma_f32_16x16x32_bf16 v[126:129], v[132:135], v[208:211], v[126:129]
	v_mfma_f32_16x16x32_bf16 v[110:113], v[140:143], v[208:211], v[110:113]
	v_mfma_f32_16x16x32_bf16 v[122:125], v[132:135], v[216:219], v[122:125]
	v_mfma_f32_16x16x32_bf16 v[106:109], v[140:143], v[216:219], v[106:109]
	v_mfma_f32_16x16x32_bf16 v[118:121], v[136:139], v[196:199], v[118:121]
	v_mfma_f32_16x16x32_bf16 v[102:105], v[144:147], v[196:199], v[102:105]
	v_mfma_f32_16x16x32_bf16 v[114:117], v[136:139], v[204:207], v[114:117]
	v_mfma_f32_16x16x32_bf16 v[98:101], v[144:147], v[204:207], v[98:101]
	v_mfma_f32_16x16x32_bf16 v[126:129], v[136:139], v[212:215], v[126:129]
	v_mfma_f32_16x16x32_bf16 v[110:113], v[144:147], v[212:215], v[110:113]
	v_mfma_f32_16x16x32_bf16 v[122:125], v[136:139], v[220:223], v[122:125]
	v_mfma_f32_16x16x32_bf16 v[106:109], v[144:147], v[220:223], v[106:109]
	v_mfma_f32_16x16x32_bf16 v[62:65], v[148:151], v[192:195], v[62:65]
	v_mfma_f32_16x16x32_bf16 v[38:41], v[156:159], v[192:195], v[38:41]
	v_mfma_f32_16x16x32_bf16 v[58:61], v[148:151], v[200:203], v[58:61]
	v_mfma_f32_16x16x32_bf16 v[34:37], v[156:159], v[200:203], v[34:37]
	v_mfma_f32_16x16x32_bf16 v[74:77], v[148:151], v[208:211], v[74:77]
	v_mfma_f32_16x16x32_bf16 v[54:57], v[156:159], v[208:211], v[54:57]
	v_mfma_f32_16x16x32_bf16 v[70:73], v[148:151], v[216:219], v[70:73]
	v_mfma_f32_16x16x32_bf16 v[46:49], v[156:159], v[216:219], v[46:49]
	v_mfma_f32_16x16x32_bf16 v[62:65], v[152:155], v[196:199], v[62:65]
	v_mfma_f32_16x16x32_bf16 v[38:41], v[184:187], v[196:199], v[38:41]
	v_mfma_f32_16x16x32_bf16 v[58:61], v[152:155], v[204:207], v[58:61]
	v_mfma_f32_16x16x32_bf16 v[34:37], v[184:187], v[204:207], v[34:37]
	v_mfma_f32_16x16x32_bf16 v[74:77], v[152:155], v[212:215], v[74:77]
	v_mfma_f32_16x16x32_bf16 v[54:57], v[184:187], v[212:215], v[54:57]
	v_mfma_f32_16x16x32_bf16 v[70:73], v[152:155], v[220:223], v[70:73]
	v_mfma_f32_16x16x32_bf16 v[46:49], v[184:187], v[220:223], v[46:49]
	s_barrier
	s_add_u32 s13, s13, 0x100
	s_addc_u32 s53, s53, 0
	s_add_u32 s60, s60, 0x800000
	s_addc_u32 s61, s61, 0
	s_cmp_ge_i32 s92, s83
	s_cbranch_scc0 .LBB0_738

.LBB0_1009:
	v_add_u32_e32 v0, s64, v187
	ds_read_b128 v[130:133], v0
	ds_read_b128 v[134:137], v0 offset:1024
	ds_read_b128 v[138:141], v0 offset:2048
	ds_read_b128 v[142:145], v0 offset:3072
	v_add_u32_e32 v0, s65, v187
	ds_read_b128 v[146:149], v0
	ds_read_b128 v[150:153], v0 offset:1024
	ds_read_b128 v[178:181], v0 offset:2048
	ds_read_b128 v[182:185], v0 offset:3072
	s_add_i32 s35, s42, 2
	s_add_u32 s43, s36, 0x3fc000
	s_addc_u32 s44, s37, 0
	s_cmp_eq_u32 s61, s42
	s_cselect_b32 s46, s28, s43
	s_cselect_b32 s47, s29, s44
	s_cselect_b32 s44, s30, s11
	s_cselect_b32 s45, s31, s27
	s_add_u32 s42, s46, 0x400000
	s_addc_u32 s43, s47, 0
	v_lshl_add_u64 v[0:1], s[36:37], 0, v[168:169]
	s_add_i32 m0, s51, 0xc000
	ds_read_b128 v[220:223], v215
	ds_read_b128 v[224:227], v215 offset:1024
	ds_read_b128 v[228:231], v215 offset:2048
	ds_read_b128 v[232:235], v215 offset:3072
	ds_read_b128 v[236:239], v215 offset:4096
	ds_read_b128 v[240:243], v215 offset:5120
	ds_read_b128 v[244:247], v215 offset:6144
	ds_read_b128 v[248:251], v215 offset:7168
	global_load_lds_dwordx4 v[0:1], off
	v_lshl_add_u64 v[0:1], s[36:37], 0, v[170:171]
	s_add_i32 m0, s51, 0xe000
	s_nop 0
	global_load_lds_dwordx4 v[0:1], off
	s_waitcnt vmcnt(8)
	s_waitcnt lgkmcnt(0)
	s_barrier
	s_waitcnt lgkmcnt(0)
	v_mfma_f32_16x16x32_bf16 v[114:117], v[130:133], v[220:223], v[114:117]
	v_mfma_f32_16x16x32_bf16 v[118:121], v[138:141], v[220:223], v[118:121]
	v_mfma_f32_16x16x32_bf16 v[110:113], v[130:133], v[228:231], v[110:113]
	v_mfma_f32_16x16x32_bf16 v[102:105], v[138:141], v[228:231], v[102:105]
	v_mfma_f32_16x16x32_bf16 v[94:97], v[130:133], v[236:239], v[94:97]
	v_mfma_f32_16x16x32_bf16 v[86:89], v[138:141], v[236:239], v[86:89]
	v_mfma_f32_16x16x32_bf16 v[78:81], v[130:133], v[244:247], v[78:81]
	v_mfma_f32_16x16x32_bf16 v[70:73], v[138:141], v[244:247], v[70:73]
	v_mfma_f32_16x16x32_bf16 v[114:117], v[134:137], v[224:227], v[114:117]
	v_mfma_f32_16x16x32_bf16 v[118:121], v[142:145], v[224:227], v[118:121]
	v_mfma_f32_16x16x32_bf16 v[110:113], v[134:137], v[232:235], v[110:113]
	v_mfma_f32_16x16x32_bf16 v[102:105], v[142:145], v[232:235], v[102:105]
	v_mfma_f32_16x16x32_bf16 v[94:97], v[134:137], v[240:243], v[94:97]
	v_mfma_f32_16x16x32_bf16 v[86:89], v[142:145], v[240:243], v[86:89]
	v_mfma_f32_16x16x32_bf16 v[78:81], v[134:137], v[248:251], v[78:81]
	v_mfma_f32_16x16x32_bf16 v[70:73], v[142:145], v[248:251], v[70:73]
	v_mfma_f32_16x16x32_bf16 v[126:129], v[146:149], v[220:223], v[126:129]
	v_mfma_f32_16x16x32_bf16 v[122:125], v[178:181], v[220:223], v[122:125]
	v_mfma_f32_16x16x32_bf16 v[106:109], v[146:149], v[228:231], v[106:109]
	v_mfma_f32_16x16x32_bf16 v[98:101], v[178:181], v[228:231], v[98:101]
	v_mfma_f32_16x16x32_bf16 v[90:93], v[146:149], v[236:239], v[90:93]
	v_mfma_f32_16x16x32_bf16 v[82:85], v[178:181], v[236:239], v[82:85]
	v_mfma_f32_16x16x32_bf16 v[74:77], v[146:149], v[244:247], v[74:77]
	v_mfma_f32_16x16x32_bf16 v[66:69], v[178:181], v[244:247], v[66:69]
	v_mfma_f32_16x16x32_bf16 v[126:129], v[150:153], v[224:227], v[126:129]
	v_mfma_f32_16x16x32_bf16 v[122:125], v[182:185], v[224:227], v[122:125]
	v_mfma_f32_16x16x32_bf16 v[106:109], v[150:153], v[232:235], v[106:109]
	v_mfma_f32_16x16x32_bf16 v[98:101], v[182:185], v[232:235], v[98:101]
	v_mfma_f32_16x16x32_bf16 v[90:93], v[150:153], v[240:243], v[90:93]
	v_mfma_f32_16x16x32_bf16 v[82:85], v[182:185], v[240:243], v[82:85]
	v_mfma_f32_16x16x32_bf16 v[74:77], v[150:153], v[248:251], v[74:77]
	v_mfma_f32_16x16x32_bf16 v[66:69], v[182:185], v[248:251], v[66:69]
	s_barrier
	s_add_i32 s69, s64, s49
	v_lshl_add_u64 v[252:253], s[44:45], 0, v[156:157]
	s_mov_b32 m0, s69
	ds_read_b128 v[220:223], v215 offset:16384
	ds_read_b128 v[224:227], v215 offset:17408
	ds_read_b128 v[228:231], v215 offset:18432
	ds_read_b128 v[232:235], v215 offset:19456
	ds_read_b128 v[236:239], v215 offset:20480
	ds_read_b128 v[240:243], v215 offset:21504
	ds_read_b128 v[244:247], v215 offset:22528
	ds_read_b128 v[248:251], v215 offset:23552
	global_load_lds_dwordx4 v[252:253], off
	s_add_i32 m0, s69, 0x2000
	s_add_u32 s70, s44, 0xb0000
	v_lshl_add_u64 v[172:173], s[44:45], 0, v[160:161]
	s_addc_u32 s71, s45, 0
	s_add_i32 s69, s65, s49
	global_load_lds_dwordx4 v[172:173], off
	v_lshl_add_u64 v[0:1], s[70:71], 0, v[156:157]
	s_mov_b32 m0, s69
	s_nop 0
	global_load_lds_dwordx4 v[0:1], off
	v_lshl_add_u64 v[0:1], s[70:71], 0, v[160:161]
	s_add_i32 m0, s69, 0x2000
	s_nop 0
	global_load_lds_dwordx4 v[0:1], off
	v_lshl_add_u64 v[0:1], s[46:47], 0, v[154:155]
	s_mov_b32 m0, s51
	s_nop 0
	global_load_lds_dwordx4 v[0:1], off
	v_lshl_add_u64 v[0:1], s[46:47], 0, v[158:159]
	s_mov_b32 m0, s52
	s_nop 0
	global_load_lds_dwordx4 v[0:1], off
	s_waitcnt vmcnt(8)
	s_waitcnt lgkmcnt(0)
	s_barrier
	s_waitcnt lgkmcnt(0)
	v_mfma_f32_16x16x32_bf16 v[50:53], v[130:133], v[220:223], v[50:53]
	v_mfma_f32_16x16x32_bf16 v[54:57], v[138:141], v[220:223], v[54:57]
	v_mfma_f32_16x16x32_bf16 v[46:49], v[130:133], v[228:231], v[46:49]
	v_mfma_f32_16x16x32_bf16 v[38:41], v[138:141], v[228:231], v[38:41]
	v_mfma_f32_16x16x32_bf16 v[30:33], v[130:133], v[236:239], v[30:33]
	v_mfma_f32_16x16x32_bf16 v[22:25], v[138:141], v[236:239], v[22:25]
	v_mfma_f32_16x16x32_bf16 v[14:17], v[130:133], v[244:247], v[14:17]
	v_mfma_f32_16x16x32_bf16 v[6:9], v[138:141], v[244:247], v[6:9]
	v_mfma_f32_16x16x32_bf16 v[50:53], v[134:137], v[224:227], v[50:53]
	v_mfma_f32_16x16x32_bf16 v[54:57], v[142:145], v[224:227], v[54:57]
	v_mfma_f32_16x16x32_bf16 v[46:49], v[134:137], v[232:235], v[46:49]
	v_mfma_f32_16x16x32_bf16 v[38:41], v[142:145], v[232:235], v[38:41]
	v_mfma_f32_16x16x32_bf16 v[30:33], v[134:137], v[240:243], v[30:33]
	v_mfma_f32_16x16x32_bf16 v[22:25], v[142:145], v[240:243], v[22:25]
	v_mfma_f32_16x16x32_bf16 v[14:17], v[134:137], v[248:251], v[14:17]
	v_mfma_f32_16x16x32_bf16 v[6:9], v[142:145], v[248:251], v[6:9]
	v_mfma_f32_16x16x32_bf16 v[62:65], v[146:149], v[220:223], v[62:65]
	v_mfma_f32_16x16x32_bf16 v[58:61], v[178:181], v[220:223], v[58:61]
	v_mfma_f32_16x16x32_bf16 v[42:45], v[146:149], v[228:231], v[42:45]
	v_mfma_f32_16x16x32_bf16 v[34:37], v[178:181], v[228:231], v[34:37]
	v_mfma_f32_16x16x32_bf16 v[26:29], v[146:149], v[236:239], v[26:29]
	v_mfma_f32_16x16x32_bf16 v[18:21], v[178:181], v[236:239], v[18:21]
	v_mfma_f32_16x16x32_bf16 v[10:13], v[146:149], v[244:247], v[10:13]
	v_mfma_f32_16x16x32_bf16 v[0:3], v[178:181], v[244:247], v[2:5]
	v_mfma_f32_16x16x32_bf16 v[62:65], v[150:153], v[224:227], v[62:65]
	v_mfma_f32_16x16x32_bf16 v[58:61], v[182:185], v[224:227], v[58:61]
	v_mfma_f32_16x16x32_bf16 v[42:45], v[150:153], v[232:235], v[42:45]
	v_mfma_f32_16x16x32_bf16 v[34:37], v[182:185], v[232:235], v[34:37]
	v_mfma_f32_16x16x32_bf16 v[26:29], v[150:153], v[240:243], v[26:29]
	v_mfma_f32_16x16x32_bf16 v[18:21], v[182:185], v[240:243], v[18:21]
	v_mfma_f32_16x16x32_bf16 v[10:13], v[150:153], v[248:251], v[10:13]
	v_mfma_f32_16x16x32_bf16 v[0:3], v[182:185], v[248:251], v[0:3]
	s_barrier
	s_add_i32 s69, 0, 0x18000
	v_add_u32_e32 v4, s69, v187
	s_add_i32 s70, 0, 0x1c000
	ds_read_b128 v[130:133], v4
	ds_read_b128 v[134:137], v4 offset:1024
	ds_read_b128 v[138:141], v4 offset:2048
	ds_read_b128 v[142:145], v4 offset:3072
	v_add_u32_e32 v4, s70, v187
	ds_read_b128 v[146:149], v4
	ds_read_b128 v[150:153], v4 offset:1024
	ds_read_b128 v[178:181], v4 offset:2048
	ds_read_b128 v[182:185], v4 offset:3072
	s_add_u32 s46, s46, 0x4000
	s_addc_u32 s47, s47, 0
	s_mov_b32 m0, s53
	v_lshl_add_u64 v[4:5], s[46:47], 0, v[154:155]
	ds_read_b128 v[220:223], v215 offset:32768
	ds_read_b128 v[224:227], v215 offset:33792
	ds_read_b128 v[228:231], v215 offset:34816
	ds_read_b128 v[232:235], v215 offset:35840
	ds_read_b128 v[236:239], v215 offset:36864
	ds_read_b128 v[240:243], v215 offset:37888
	ds_read_b128 v[244:247], v215 offset:38912
	ds_read_b128 v[248:251], v215 offset:39936
	global_load_lds_dwordx4 v[4:5], off
	v_lshl_add_u64 v[4:5], s[46:47], 0, v[158:159]
	s_mov_b32 m0, s54
	s_nop 0
	global_load_lds_dwordx4 v[4:5], off
	s_waitcnt vmcnt(8)
	s_waitcnt lgkmcnt(0)
	s_barrier
	s_waitcnt lgkmcnt(0)
	v_mfma_f32_16x16x32_bf16 v[114:117], v[130:133], v[220:223], v[114:117]
	v_mfma_f32_16x16x32_bf16 v[118:121], v[138:141], v[220:223], v[118:121]
	v_mfma_f32_16x16x32_bf16 v[110:113], v[130:133], v[228:231], v[110:113]
	v_mfma_f32_16x16x32_bf16 v[102:105], v[138:141], v[228:231], v[102:105]
	v_mfma_f32_16x16x32_bf16 v[94:97], v[130:133], v[236:239], v[94:97]
	v_mfma_f32_16x16x32_bf16 v[86:89], v[138:141], v[236:239], v[86:89]
	v_mfma_f32_16x16x32_bf16 v[78:81], v[130:133], v[244:247], v[78:81]
	v_mfma_f32_16x16x32_bf16 v[70:73], v[138:141], v[244:247], v[70:73]
	v_mfma_f32_16x16x32_bf16 v[114:117], v[134:137], v[224:227], v[114:117]
	v_mfma_f32_16x16x32_bf16 v[118:121], v[142:145], v[224:227], v[118:121]
	v_mfma_f32_16x16x32_bf16 v[110:113], v[134:137], v[232:235], v[110:113]
	v_mfma_f32_16x16x32_bf16 v[102:105], v[142:145], v[232:235], v[102:105]
	v_mfma_f32_16x16x32_bf16 v[94:97], v[134:137], v[240:243], v[94:97]
	v_mfma_f32_16x16x32_bf16 v[86:89], v[142:145], v[240:243], v[86:89]
	v_mfma_f32_16x16x32_bf16 v[78:81], v[134:137], v[248:251], v[78:81]
	v_mfma_f32_16x16x32_bf16 v[70:73], v[142:145], v[248:251], v[70:73]
	v_mfma_f32_16x16x32_bf16 v[126:129], v[146:149], v[220:223], v[126:129]
	v_mfma_f32_16x16x32_bf16 v[122:125], v[178:181], v[220:223], v[122:125]
	v_mfma_f32_16x16x32_bf16 v[106:109], v[146:149], v[228:231], v[106:109]
	v_mfma_f32_16x16x32_bf16 v[98:101], v[178:181], v[228:231], v[98:101]
	v_mfma_f32_16x16x32_bf16 v[90:93], v[146:149], v[236:239], v[90:93]
	v_mfma_f32_16x16x32_bf16 v[82:85], v[178:181], v[236:239], v[82:85]
	v_mfma_f32_16x16x32_bf16 v[74:77], v[146:149], v[244:247], v[74:77]
	v_mfma_f32_16x16x32_bf16 v[66:69], v[178:181], v[244:247], v[66:69]
	v_mfma_f32_16x16x32_bf16 v[126:129], v[150:153], v[224:227], v[126:129]
	v_mfma_f32_16x16x32_bf16 v[122:125], v[182:185], v[224:227], v[122:125]
	v_mfma_f32_16x16x32_bf16 v[106:109], v[150:153], v[232:235], v[106:109]
	v_mfma_f32_16x16x32_bf16 v[98:101], v[182:185], v[232:235], v[98:101]
	v_mfma_f32_16x16x32_bf16 v[90:93], v[150:153], v[240:243], v[90:93]
	v_mfma_f32_16x16x32_bf16 v[82:85], v[182:185], v[240:243], v[82:85]
	v_mfma_f32_16x16x32_bf16 v[74:77], v[150:153], v[248:251], v[74:77]
	v_mfma_f32_16x16x32_bf16 v[66:69], v[182:185], v[248:251], v[66:69]
	s_barrier
	s_add_i32 s46, s69, s49
	v_lshl_add_u64 v[4:5], v[252:253], 0, s[18:19]
	s_mov_b32 m0, s46
	ds_read_b128 v[220:223], v215 offset:49152
	ds_read_b128 v[224:227], v215 offset:50176
	ds_read_b128 v[228:231], v215 offset:51200
	ds_read_b128 v[232:235], v215 offset:52224
	ds_read_b128 v[236:239], v215 offset:53248
	ds_read_b128 v[240:243], v215 offset:54272
	ds_read_b128 v[244:247], v215 offset:55296
	ds_read_b128 v[248:251], v215 offset:56320
	global_load_lds_dwordx4 v[4:5], off
	s_add_i32 m0, s46, 0x2000
	s_add_u32 s44, s44, 0xb0080
	v_lshl_add_u64 v[4:5], v[172:173], 0, s[18:19]
	s_addc_u32 s45, s45, 0
	s_add_i32 s46, s70, s49
	global_load_lds_dwordx4 v[4:5], off
	v_lshl_add_u64 v[4:5], s[44:45], 0, v[156:157]
	s_mov_b32 m0, s46
	s_nop 0
	global_load_lds_dwordx4 v[4:5], off
	v_lshl_add_u64 v[4:5], s[44:45], 0, v[160:161]
	s_add_i32 m0, s46, 0x2000
	s_nop 0
	global_load_lds_dwordx4 v[4:5], off
	v_lshl_add_u64 v[4:5], s[42:43], 0, v[154:155]
	s_mov_b32 m0, s59
	s_nop 0
	global_load_lds_dwordx4 v[4:5], off
	v_lshl_add_u64 v[4:5], s[42:43], 0, v[158:159]
	s_mov_b32 m0, s60
	s_nop 0
	global_load_lds_dwordx4 v[4:5], off
	s_waitcnt vmcnt(8)
	s_waitcnt lgkmcnt(0)
	s_barrier
	s_waitcnt lgkmcnt(0)
	v_mfma_f32_16x16x32_bf16 v[50:53], v[130:133], v[220:223], v[50:53]
	v_mfma_f32_16x16x32_bf16 v[54:57], v[138:141], v[220:223], v[54:57]
	v_mfma_f32_16x16x32_bf16 v[46:49], v[130:133], v[228:231], v[46:49]
	v_mfma_f32_16x16x32_bf16 v[38:41], v[138:141], v[228:231], v[38:41]
	v_mfma_f32_16x16x32_bf16 v[30:33], v[130:133], v[236:239], v[30:33]
	v_mfma_f32_16x16x32_bf16 v[22:25], v[138:141], v[236:239], v[22:25]
	v_mfma_f32_16x16x32_bf16 v[14:17], v[130:133], v[244:247], v[14:17]
	v_mfma_f32_16x16x32_bf16 v[4:7], v[138:141], v[244:247], v[6:9]
	v_mfma_f32_16x16x32_bf16 v[50:53], v[134:137], v[224:227], v[50:53]
	v_mfma_f32_16x16x32_bf16 v[54:57], v[142:145], v[224:227], v[54:57]
	v_mfma_f32_16x16x32_bf16 v[46:49], v[134:137], v[232:235], v[46:49]
	v_mfma_f32_16x16x32_bf16 v[38:41], v[142:145], v[232:235], v[38:41]
	v_mfma_f32_16x16x32_bf16 v[30:33], v[134:137], v[240:243], v[30:33]
	v_mfma_f32_16x16x32_bf16 v[22:25], v[142:145], v[240:243], v[22:25]
	v_mfma_f32_16x16x32_bf16 v[14:17], v[134:137], v[248:251], v[14:17]
	v_mfma_f32_16x16x32_bf16 v[6:9], v[142:145], v[248:251], v[4:7]
	v_mfma_f32_16x16x32_bf16 v[62:65], v[146:149], v[220:223], v[62:65]
	v_mfma_f32_16x16x32_bf16 v[58:61], v[178:181], v[220:223], v[58:61]
	v_mfma_f32_16x16x32_bf16 v[42:45], v[146:149], v[228:231], v[42:45]
	v_mfma_f32_16x16x32_bf16 v[34:37], v[178:181], v[228:231], v[34:37]
	v_mfma_f32_16x16x32_bf16 v[26:29], v[146:149], v[236:239], v[26:29]
	v_mfma_f32_16x16x32_bf16 v[18:21], v[178:181], v[236:239], v[18:21]
	v_mfma_f32_16x16x32_bf16 v[10:13], v[146:149], v[244:247], v[10:13]
	v_mfma_f32_16x16x32_bf16 v[0:3], v[178:181], v[244:247], v[0:3]
	v_mfma_f32_16x16x32_bf16 v[62:65], v[150:153], v[224:227], v[62:65]
	v_mfma_f32_16x16x32_bf16 v[58:61], v[182:185], v[224:227], v[58:61]
	v_mfma_f32_16x16x32_bf16 v[42:45], v[150:153], v[232:235], v[42:45]
	v_mfma_f32_16x16x32_bf16 v[34:37], v[182:185], v[232:235], v[34:37]
	v_mfma_f32_16x16x32_bf16 v[26:29], v[150:153], v[240:243], v[26:29]
	v_mfma_f32_16x16x32_bf16 v[18:21], v[182:185], v[240:243], v[18:21]
	v_mfma_f32_16x16x32_bf16 v[10:13], v[150:153], v[248:251], v[10:13]
	v_mfma_f32_16x16x32_bf16 v[2:5], v[182:185], v[248:251], v[0:3]
	s_barrier
	s_add_u32 s11, s11, 0x100
	s_addc_u32 s27, s27, 0
	s_add_u32 s36, s36, 0x800000
	s_addc_u32 s37, s37, 0
	s_cmp_ge_i32 s35, s58
	s_mov_b32 s42, s35
	s_cbranch_scc0 .LBB0_1009
	v_mov_b64_e32 v[234:235], v[174:175]
	s_and_b64 vcc, exec, s[22:23]
	s_cbranch_vccnz .LBB0_980
	s_branch .LBB0_981
